# combo2 + MFMA order regrouped so the A-fragment operand (SrcB) stays fixed for 4 consecutive MFMAs in 14 of 20 phases
# speedup vs baseline: 1.0056x; 1.0056x over previous
; #define PG8_STAGE(bufoff, gbase, voff) do { _Pragma("unroll") for (int _i = 0; _i < 2; ++_i) \
;         __builtin_amdgcn_global_load_lds((const unsigned*)((const char*)(gbase) + (voff)[_i]), (PG8_LAS unsigned*)(lds + (bufoff) + ldsw + _i * 8192), 16, 0, 0); } while (0)
; #define PG8_LDA(dst, b, h) do { _Pragma("unroll") for (int m = 0; m < 4; ++m) _Pragma("unroll") for (int k = 0; k < 2; ++k) dst[m][k] = *(const PG8_LAS bf16x8*)(lds + PG8_SA(b, h) + aoff + m * 2048 + k * 1024); } while (0)
; #define PG8_LDB(dst, b, h) do { _Pragma("unroll") for (int n = 0; n < 2; ++n) _Pragma("unroll") for (int k = 0; k < 2; ++k) dst[n][k] = *(const PG8_LAS bf16x8*)(lds + PG8_SB(b, h) + boff + n * 2048 + k * 1024); } while (0)
; #define PG8_MMA(ai, bj, At, Bt) do { __builtin_amdgcn_s_setprio(1); _Pragma("unroll") for (int m = 0; m < 4; ++m) _Pragma("unroll") for (int n = 0; n < 2; ++n) _Pragma("unroll") for (int k = 0; k < 2; ++k) \
;         acc[ai][bj][m][n] = __builtin_amdgcn_mfma_f32_16x16x32_bf16(Bt[n][k], At[m][k], acc[ai][bj][m][n], 0, 0, 0); __builtin_amdgcn_s_setprio(0); } while (0)
; #define PG8_WAIT_V(n) asm volatile("s_waitcnt vmcnt(" #n ")" ::: "memory")
; #define PG8_BAR __builtin_amdgcn_s_barrier()
; template <class Epi, class Sched, bool ALIGN_EPI = false, bool SP2 = false>
; __device__ __forceinline__ void gemm_phase(PG8_LAS unsigned char* lds, const Gemm g, const Sched& S, const Epi& E, const int tid) {
;     ...
;             const char* a1 = cA + (size_t)(t + 1) * kstep;
;             const char* a2 = last ? nA : cA + (size_t)(t + 2) * kstep; const char* b2 = last ? nB : cB + (size_t)(t + 2) * kstep;
;             const char* a3 = a2 + kstep; const char* b3 = b2 + kstep;
;             if (last && has_next) S.a_ready(nxt);
;             if (last) E.prefetch(lds + EPI_LDS_OFF + wid * 1024, cur, wr, wc, lane);
;             if constexpr (SP2) {
;             PG8_LDB(B0, 0, 0); PG8_LDB(B1, 0, 1); PG8_SCHED; PG8_LDA(At, 0, 0); PG8_STAGE(PG8_SA(1, 1), a1 + hstep, voffA);
;             PG8_WAIT_V(8); PG8_WAIT_L(0); PG8_BAR; PG8_MMA(0, 0, At, B0); PG8_MMA(0, 1, At, B1); PG8_BAR; PG8_SCHED;
;             PG8_LDA(At, 0, 1); PG8_STAGE(PG8_SB(0, 0), b2, voffB); PG8_STAGE(PG8_SB(0, 1), b2 + hstep, voffB); PG8_STAGE(PG8_SA(0, 0), a2, voffA);
;             PG8_WAIT_V(8); PG8_WAIT_L(0); PG8_BAR; PG8_MMA(1, 0, At, B0); PG8_MMA(1, 1, At, B1); PG8_BAR; PG8_SCHED;
.LBB0_42:
	s_add_u32 s18, s16, 0x100
	s_addc_u32 s19, s17, 0
	s_and_b64 s[20:21], s[20:21], exec
	s_cselect_b32 s23, s9, s19
	s_cselect_b32 s22, s8, s18
	s_cselect_b32 s21, s15, s74
	s_cselect_b32 s20, s14, s55
	s_add_i32 s3, 0, 0x10000
	s_add_i32 s42, 0, 0x14000
	v_add_u32_e32 v146, s3, v224
	v_add_u32_e32 v162, s42, v224
	ds_read_b128 v[134:137], v146
	ds_read_b128 v[138:141], v146 offset:1024
	ds_read_b128 v[142:145], v146 offset:2048
	ds_read_b128 v[146:149], v146 offset:3072
	ds_read_b128 v[150:153], v162
	ds_read_b128 v[154:157], v162 offset:1024
	ds_read_b128 v[158:161], v162 offset:2048
	ds_read_b128 v[172:175], v162 offset:3072
	v_lshl_add_u64 v[162:163], s[16:17], 0, v[168:169]
	s_add_i32 m0, s27, 0xc000
	ds_read_b128 v[176:179], v228
	ds_read_b128 v[180:183], v228 offset:1024
	ds_read_b128 v[186:189], v228 offset:2048
	ds_read_b128 v[190:193], v228 offset:3072
	ds_read_b128 v[194:197], v228 offset:4096
	ds_read_b128 v[198:201], v228 offset:5120
	ds_read_b128 v[202:205], v228 offset:6144
	ds_read_b128 v[206:209], v228 offset:7168
	global_load_lds_dwordx4 v[162:163], off
	v_lshl_add_u64 v[162:163], s[16:17], 0, v[170:171]
	s_add_i32 m0, s27, 0xe000
	s_nop 0
	global_load_lds_dwordx4 v[162:163], off
	s_waitcnt vmcnt(8)
	s_waitcnt lgkmcnt(0)
	s_setprio 1
	s_barrier
	v_mfma_f32_16x16x32_bf16 v[128:131], v[134:137], v[176:179], v[128:131]
	v_mfma_f32_16x16x32_bf16 v[124:127], v[142:145], v[176:179], v[124:127]
	v_mfma_f32_16x16x32_bf16 v[120:123], v[150:153], v[176:179], v[120:123]
	v_mfma_f32_16x16x32_bf16 v[116:119], v[158:161], v[176:179], v[116:119]
	v_mfma_f32_16x16x32_bf16 v[112:115], v[134:137], v[186:189], v[112:115]
	v_mfma_f32_16x16x32_bf16 v[108:111], v[142:145], v[186:189], v[108:111]
	v_mfma_f32_16x16x32_bf16 v[104:107], v[150:153], v[186:189], v[104:107]
	v_mfma_f32_16x16x32_bf16 v[100:103], v[158:161], v[186:189], v[100:103]
	v_mfma_f32_16x16x32_bf16 v[96:99], v[134:137], v[194:197], v[96:99]
	v_mfma_f32_16x16x32_bf16 v[92:95], v[142:145], v[194:197], v[92:95]
	v_mfma_f32_16x16x32_bf16 v[88:91], v[150:153], v[194:197], v[88:91]
	v_mfma_f32_16x16x32_bf16 v[84:87], v[158:161], v[194:197], v[84:87]
	v_mfma_f32_16x16x32_bf16 v[80:83], v[134:137], v[202:205], v[80:83]
	v_mfma_f32_16x16x32_bf16 v[76:79], v[142:145], v[202:205], v[76:79]
	v_mfma_f32_16x16x32_bf16 v[72:75], v[150:153], v[202:205], v[72:75]
	v_mfma_f32_16x16x32_bf16 v[68:71], v[158:161], v[202:205], v[68:71]
	s_setprio 0
	s_setprio 1
	v_mfma_f32_16x16x32_bf16 v[128:131], v[138:141], v[180:183], v[128:131]
	v_mfma_f32_16x16x32_bf16 v[124:127], v[146:149], v[180:183], v[124:127]
	v_mfma_f32_16x16x32_bf16 v[120:123], v[154:157], v[180:183], v[120:123]
	v_mfma_f32_16x16x32_bf16 v[116:119], v[172:175], v[180:183], v[116:119]
	v_mfma_f32_16x16x32_bf16 v[112:115], v[138:141], v[190:193], v[112:115]
	v_mfma_f32_16x16x32_bf16 v[108:111], v[146:149], v[190:193], v[108:111]
	v_mfma_f32_16x16x32_bf16 v[104:107], v[154:157], v[190:193], v[104:107]
	v_mfma_f32_16x16x32_bf16 v[100:103], v[172:175], v[190:193], v[100:103]
	v_mfma_f32_16x16x32_bf16 v[96:99], v[138:141], v[198:201], v[96:99]
	v_mfma_f32_16x16x32_bf16 v[92:95], v[146:149], v[198:201], v[92:95]
	v_mfma_f32_16x16x32_bf16 v[88:91], v[154:157], v[198:201], v[88:91]
	v_mfma_f32_16x16x32_bf16 v[84:87], v[172:175], v[198:201], v[84:87]
	v_mfma_f32_16x16x32_bf16 v[80:83], v[138:141], v[206:209], v[80:83]
	v_mfma_f32_16x16x32_bf16 v[76:79], v[146:149], v[206:209], v[76:79]
	v_mfma_f32_16x16x32_bf16 v[72:75], v[154:157], v[206:209], v[72:75]
	v_mfma_f32_16x16x32_bf16 v[68:71], v[172:175], v[206:209], v[68:71]
	s_setprio 0
	s_barrier
	s_add_i32 s3, s3, s26
	v_lshl_add_u64 v[162:163], s[20:21], 0, v[2:3]
	s_mov_b32 m0, s3
	ds_read_b128 v[176:179], v228 offset:16384
	ds_read_b128 v[180:183], v228 offset:17408
	ds_read_b128 v[186:189], v228 offset:18432
	ds_read_b128 v[190:193], v228 offset:19456
	ds_read_b128 v[194:197], v228 offset:20480
	ds_read_b128 v[198:201], v228 offset:21504
	ds_read_b128 v[202:205], v228 offset:22528
	ds_read_b128 v[206:209], v228 offset:23552
	global_load_lds_dwordx4 v[162:163], off
	s_add_i32 m0, s3, 0x2000
	s_add_u32 s16, s20, 0x160000
	v_lshl_add_u64 v[210:211], s[20:21], 0, v[166:167]
	s_addc_u32 s17, s21, 0
	s_add_i32 s3, s42, s26
	global_load_lds_dwordx4 v[210:211], off
	v_lshl_add_u64 v[212:213], s[16:17], 0, v[2:3]
	s_mov_b32 m0, s3
	v_lshl_add_u64 v[214:215], s[22:23], 0, v[164:165]
	global_load_lds_dwordx4 v[212:213], off
	v_lshl_add_u64 v[212:213], s[16:17], 0, v[166:167]
	s_add_i32 m0, s3, 0x2000
	s_nop 0
	global_load_lds_dwordx4 v[212:213], off
	v_lshl_add_u64 v[212:213], s[22:23], 0, v[0:1]
	s_mov_b32 m0, s27
	s_nop 0
	global_load_lds_dwordx4 v[212:213], off
	s_mov_b32 m0, s28
	s_nop 0
	global_load_lds_dwordx4 v[214:215], off
	s_waitcnt vmcnt(8)
	s_waitcnt lgkmcnt(0)
	s_setprio 1
	s_barrier
; #define PG8_STAGE(bufoff, gbase, voff) do { _Pragma("unroll") for (int _i = 0; _i < 2; ++_i) \
;         __builtin_amdgcn_global_load_lds((const unsigned*)((const char*)(gbase) + (voff)[_i]), (PG8_LAS unsigned*)(lds + (bufoff) + ldsw + _i * 8192), 16, 0, 0); } while (0)
; #define PG8_LDA(dst, b, h) do { _Pragma("unroll") for (int m = 0; m < 4; ++m) _Pragma("unroll") for (int k = 0; k < 2; ++k) dst[m][k] = *(const PG8_LAS bf16x8*)(lds + PG8_SA(b, h) + aoff + m * 2048 + k * 1024); } while (0)
; #define PG8_LDB(dst, b, h) do { _Pragma("unroll") for (int n = 0; n < 2; ++n) _Pragma("unroll") for (int k = 0; k < 2; ++k) dst[n][k] = *(const PG8_LAS bf16x8*)(lds + PG8_SB(b, h) + boff + n * 2048 + k * 1024); } while (0)
; #define PG8_MMA(ai, bj, At, Bt) do { __builtin_amdgcn_s_setprio(1); _Pragma("unroll") for (int m = 0; m < 4; ++m) _Pragma("unroll") for (int n = 0; n < 2; ++n) _Pragma("unroll") for (int k = 0; k < 2; ++k) \
;         acc[ai][bj][m][n] = __builtin_amdgcn_mfma_f32_16x16x32_bf16(Bt[n][k], At[m][k], acc[ai][bj][m][n], 0, 0, 0); __builtin_amdgcn_s_setprio(0); } while (0)
; #define PG8_WAIT_V(n) asm volatile("s_waitcnt vmcnt(" #n ")" ::: "memory")
; #define PG8_WAIT_L(n) asm volatile("s_waitcnt lgkmcnt(" #n ")" ::: "memory")
; #define PG8_BAR __builtin_amdgcn_s_barrier()
; #define PG8_SCHED __builtin_amdgcn_sched_barrier(0)
; template <class Epi, class Sched, bool ALIGN_EPI = false, bool SP2 = false>
; __device__ __forceinline__ void gemm_phase(PG8_LAS unsigned char* lds, const Gemm g, const Sched& S, const Epi& E, const int tid) {
;     ...
;             PG8_WAIT_V(8); PG8_WAIT_L(0); PG8_BAR; PG8_MMA(1, 0, At, B0); PG8_MMA(1, 1, At, B1); PG8_BAR; PG8_SCHED;
;             PG8_LDB(B0, 1, 0); PG8_LDB(B1, 1, 1); PG8_SCHED; PG8_LDA(At, 1, 0); PG8_STAGE(PG8_SA(0, 1), a2 + hstep, voffA);
;             PG8_WAIT_V(8); PG8_WAIT_L(0); PG8_BAR; PG8_MMA(0, 0, At, B0); PG8_MMA(0, 1, At, B1); PG8_BAR; PG8_SCHED;
	v_mfma_f32_16x16x32_bf16 v[64:67], v[134:137], v[176:179], v[64:67]
	v_mfma_f32_16x16x32_bf16 v[60:63], v[142:145], v[176:179], v[60:63]
	v_mfma_f32_16x16x32_bf16 v[56:59], v[150:153], v[176:179], v[56:59]
	v_mfma_f32_16x16x32_bf16 v[52:55], v[158:161], v[176:179], v[52:55]
	v_mfma_f32_16x16x32_bf16 v[48:51], v[134:137], v[186:189], v[48:51]
	v_mfma_f32_16x16x32_bf16 v[44:47], v[142:145], v[186:189], v[44:47]
	v_mfma_f32_16x16x32_bf16 v[40:43], v[150:153], v[186:189], v[40:43]
	v_mfma_f32_16x16x32_bf16 v[36:39], v[158:161], v[186:189], v[36:39]
	v_mfma_f32_16x16x32_bf16 v[32:35], v[134:137], v[194:197], v[32:35]
	v_mfma_f32_16x16x32_bf16 v[28:31], v[142:145], v[194:197], v[28:31]
	v_mfma_f32_16x16x32_bf16 v[24:27], v[150:153], v[194:197], v[24:27]
	v_mfma_f32_16x16x32_bf16 v[20:23], v[158:161], v[194:197], v[20:23]
	v_mfma_f32_16x16x32_bf16 v[16:19], v[134:137], v[202:205], v[16:19]
	v_mfma_f32_16x16x32_bf16 v[12:15], v[142:145], v[202:205], v[12:15]
	v_mfma_f32_16x16x32_bf16 v[8:11], v[150:153], v[202:205], v[8:11]
	v_mfma_f32_16x16x32_bf16 v[4:7], v[158:161], v[202:205], v[4:7]
	s_setprio 0
	s_setprio 1
	v_mfma_f32_16x16x32_bf16 v[64:67], v[138:141], v[180:183], v[64:67]
	v_mfma_f32_16x16x32_bf16 v[60:63], v[146:149], v[180:183], v[60:63]
	v_mfma_f32_16x16x32_bf16 v[56:59], v[154:157], v[180:183], v[56:59]
	v_mfma_f32_16x16x32_bf16 v[52:55], v[172:175], v[180:183], v[52:55]
	v_mfma_f32_16x16x32_bf16 v[48:51], v[138:141], v[190:193], v[48:51]
	v_mfma_f32_16x16x32_bf16 v[44:47], v[146:149], v[190:193], v[44:47]
	v_mfma_f32_16x16x32_bf16 v[40:43], v[154:157], v[190:193], v[40:43]
	v_mfma_f32_16x16x32_bf16 v[36:39], v[172:175], v[190:193], v[36:39]
	v_mfma_f32_16x16x32_bf16 v[32:35], v[138:141], v[198:201], v[32:35]
	v_mfma_f32_16x16x32_bf16 v[28:31], v[146:149], v[198:201], v[28:31]
	v_mfma_f32_16x16x32_bf16 v[24:27], v[154:157], v[198:201], v[24:27]
	v_mfma_f32_16x16x32_bf16 v[20:23], v[172:175], v[198:201], v[20:23]
	v_mfma_f32_16x16x32_bf16 v[16:19], v[138:141], v[206:209], v[16:19]
	v_mfma_f32_16x16x32_bf16 v[12:15], v[146:149], v[206:209], v[12:15]
	v_mfma_f32_16x16x32_bf16 v[8:11], v[154:157], v[206:209], v[8:11]
	v_mfma_f32_16x16x32_bf16 v[4:7], v[172:175], v[206:209], v[4:7]
	s_setprio 0
	s_barrier
	s_add_i32 s3, 0, 0x18000
	s_add_i32 s42, 0, 0x1c000
	v_add_u32_e32 v146, s3, v224
	v_add_u32_e32 v172, s42, v224
	ds_read_b128 v[134:137], v146
	ds_read_b128 v[138:141], v146 offset:1024
	ds_read_b128 v[142:145], v146 offset:2048
	ds_read_b128 v[146:149], v146 offset:3072
	ds_read_b128 v[150:153], v172
	ds_read_b128 v[154:157], v172 offset:1024
	ds_read_b128 v[158:161], v172 offset:2048
	ds_read_b128 v[172:175], v172 offset:3072
	s_add_u32 s16, s22, 0x160000
	s_addc_u32 s17, s23, 0
	s_mov_b32 m0, s29
	v_lshl_add_u64 v[216:217], s[16:17], 0, v[0:1]
	ds_read_b128 v[176:179], v228 offset:32768
	ds_read_b128 v[180:183], v228 offset:33792
	ds_read_b128 v[186:189], v228 offset:34816
	ds_read_b128 v[190:193], v228 offset:35840
	ds_read_b128 v[194:197], v228 offset:36864
	ds_read_b128 v[198:201], v228 offset:37888
	ds_read_b128 v[202:205], v228 offset:38912
	ds_read_b128 v[206:209], v228 offset:39936
	global_load_lds_dwordx4 v[216:217], off
	v_lshl_add_u64 v[216:217], s[16:17], 0, v[164:165]
	s_mov_b32 m0, s30
	s_nop 0
	global_load_lds_dwordx4 v[216:217], off
	s_waitcnt vmcnt(8)
	s_waitcnt lgkmcnt(0)
	s_setprio 1
	s_barrier
	v_mfma_f32_16x16x32_bf16 v[128:131], v[134:137], v[176:179], v[128:131]
	v_mfma_f32_16x16x32_bf16 v[124:127], v[142:145], v[176:179], v[124:127]
	v_mfma_f32_16x16x32_bf16 v[120:123], v[150:153], v[176:179], v[120:123]
	v_mfma_f32_16x16x32_bf16 v[116:119], v[158:161], v[176:179], v[116:119]
	v_mfma_f32_16x16x32_bf16 v[112:115], v[134:137], v[186:189], v[112:115]
	v_mfma_f32_16x16x32_bf16 v[108:111], v[142:145], v[186:189], v[108:111]
	v_mfma_f32_16x16x32_bf16 v[104:107], v[150:153], v[186:189], v[104:107]
	v_mfma_f32_16x16x32_bf16 v[100:103], v[158:161], v[186:189], v[100:103]
	v_mfma_f32_16x16x32_bf16 v[96:99], v[134:137], v[194:197], v[96:99]
	v_mfma_f32_16x16x32_bf16 v[92:95], v[142:145], v[194:197], v[92:95]
	v_mfma_f32_16x16x32_bf16 v[88:91], v[150:153], v[194:197], v[88:91]
	v_mfma_f32_16x16x32_bf16 v[84:87], v[158:161], v[194:197], v[84:87]
	v_mfma_f32_16x16x32_bf16 v[80:83], v[134:137], v[202:205], v[80:83]
	v_mfma_f32_16x16x32_bf16 v[76:79], v[142:145], v[202:205], v[76:79]
	v_mfma_f32_16x16x32_bf16 v[72:75], v[150:153], v[202:205], v[72:75]
	v_mfma_f32_16x16x32_bf16 v[68:71], v[158:161], v[202:205], v[68:71]
	s_setprio 0
	s_setprio 1
	v_mfma_f32_16x16x32_bf16 v[128:131], v[138:141], v[180:183], v[128:131]
	v_mfma_f32_16x16x32_bf16 v[124:127], v[146:149], v[180:183], v[124:127]
	v_mfma_f32_16x16x32_bf16 v[120:123], v[154:157], v[180:183], v[120:123]
	v_mfma_f32_16x16x32_bf16 v[116:119], v[172:175], v[180:183], v[116:119]
	v_mfma_f32_16x16x32_bf16 v[112:115], v[138:141], v[190:193], v[112:115]
	v_mfma_f32_16x16x32_bf16 v[108:111], v[146:149], v[190:193], v[108:111]
	v_mfma_f32_16x16x32_bf16 v[104:107], v[154:157], v[190:193], v[104:107]
	v_mfma_f32_16x16x32_bf16 v[100:103], v[172:175], v[190:193], v[100:103]
	v_mfma_f32_16x16x32_bf16 v[96:99], v[138:141], v[198:201], v[96:99]
	v_mfma_f32_16x16x32_bf16 v[92:95], v[146:149], v[198:201], v[92:95]
	v_mfma_f32_16x16x32_bf16 v[88:91], v[154:157], v[198:201], v[88:91]
	v_mfma_f32_16x16x32_bf16 v[84:87], v[172:175], v[198:201], v[84:87]
	v_mfma_f32_16x16x32_bf16 v[80:83], v[138:141], v[206:209], v[80:83]
	v_mfma_f32_16x16x32_bf16 v[76:79], v[146:149], v[206:209], v[76:79]
	v_mfma_f32_16x16x32_bf16 v[72:75], v[154:157], v[206:209], v[72:75]
	v_mfma_f32_16x16x32_bf16 v[68:71], v[172:175], v[206:209], v[68:71]
	s_setprio 0
	s_barrier
; #define PG8_STAGE(bufoff, gbase, voff) do { _Pragma("unroll") for (int _i = 0; _i < 2; ++_i) \
;         __builtin_amdgcn_global_load_lds((const unsigned*)((const char*)(gbase) + (voff)[_i]), (PG8_LAS unsigned*)(lds + (bufoff) + ldsw + _i * 8192), 16, 0, 0); } while (0)
; #define PG8_LDA(dst, b, h) do { _Pragma("unroll") for (int m = 0; m < 4; ++m) _Pragma("unroll") for (int k = 0; k < 2; ++k) dst[m][k] = *(const PG8_LAS bf16x8*)(lds + PG8_SA(b, h) + aoff + m * 2048 + k * 1024); } while (0)
; #define PG8_MMA(ai, bj, At, Bt) do { __builtin_amdgcn_s_setprio(1); _Pragma("unroll") for (int m = 0; m < 4; ++m) _Pragma("unroll") for (int n = 0; n < 2; ++n) _Pragma("unroll") for (int k = 0; k < 2; ++k) \
;         acc[ai][bj][m][n] = __builtin_amdgcn_mfma_f32_16x16x32_bf16(Bt[n][k], At[m][k], acc[ai][bj][m][n], 0, 0, 0); __builtin_amdgcn_s_setprio(0); } while (0)
; #define PG8_WAIT_V(n) asm volatile("s_waitcnt vmcnt(" #n ")" ::: "memory")
; #define PG8_WAIT_L(n) asm volatile("s_waitcnt lgkmcnt(" #n ")" ::: "memory")
; #define PG8_BAR __builtin_amdgcn_s_barrier()
; #define PG8_SCHED __builtin_amdgcn_sched_barrier(0)
; template <class Epi, class Sched, bool ALIGN_EPI = false, bool SP2 = false>
; __device__ __forceinline__ void gemm_phase(PG8_LAS unsigned char* lds, const Gemm g, const Sched& S, const Epi& E, const int tid) {
;     ...
;             PG8_LDA(At, 1, 1); PG8_STAGE(PG8_SB(1, 0), b3, voffB); PG8_STAGE(PG8_SB(1, 1), b3 + hstep, voffB); PG8_STAGE(PG8_SA(1, 0), a3, voffA);
;             PG8_WAIT_V(8); PG8_WAIT_L(0); PG8_BAR; PG8_MMA(1, 0, At, B0); PG8_MMA(1, 1, At, B1); PG8_BAR; PG8_SCHED;
	s_add_i32 s3, s3, s26
	v_lshl_add_u64 v[162:163], v[162:163], 0, s[46:47]
	s_mov_b32 m0, s3
	ds_read_b128 v[176:179], v228 offset:49152
	ds_read_b128 v[180:183], v228 offset:50176
	ds_read_b128 v[186:189], v228 offset:51200
	ds_read_b128 v[190:193], v228 offset:52224
	ds_read_b128 v[194:197], v228 offset:53248
	ds_read_b128 v[198:201], v228 offset:54272
	ds_read_b128 v[202:205], v228 offset:55296
	ds_read_b128 v[206:209], v228 offset:56320
	global_load_lds_dwordx4 v[162:163], off
	s_add_i32 m0, s3, 0x2000
	s_add_u32 s16, s20, 0x160080
	v_lshl_add_u64 v[162:163], v[210:211], 0, s[46:47]
	s_addc_u32 s17, s21, 0
	s_add_i32 s3, s42, s26
	global_load_lds_dwordx4 v[162:163], off
	v_lshl_add_u64 v[162:163], s[16:17], 0, v[2:3]
	s_mov_b32 m0, s3
	s_nop 0
	global_load_lds_dwordx4 v[162:163], off
	v_lshl_add_u64 v[162:163], s[16:17], 0, v[166:167]
	s_add_i32 m0, s3, 0x2000
	s_nop 0
	global_load_lds_dwordx4 v[162:163], off
	v_lshl_add_u64 v[162:163], v[212:213], 0, s[46:47]
	s_mov_b32 m0, s31
	s_nop 0
	global_load_lds_dwordx4 v[162:163], off
	v_lshl_add_u64 v[162:163], v[214:215], 0, s[46:47]
	s_mov_b32 m0, s37
	s_nop 0
	global_load_lds_dwordx4 v[162:163], off
	s_waitcnt vmcnt(8)
	s_waitcnt lgkmcnt(0)
	s_setprio 1
	s_barrier
	v_mfma_f32_16x16x32_bf16 v[64:67], v[134:137], v[176:179], v[64:67]
	v_mfma_f32_16x16x32_bf16 v[60:63], v[142:145], v[176:179], v[60:63]
	v_mfma_f32_16x16x32_bf16 v[56:59], v[150:153], v[176:179], v[56:59]
	v_mfma_f32_16x16x32_bf16 v[52:55], v[158:161], v[176:179], v[52:55]
	v_mfma_f32_16x16x32_bf16 v[48:51], v[134:137], v[186:189], v[48:51]
	v_mfma_f32_16x16x32_bf16 v[44:47], v[142:145], v[186:189], v[44:47]
	v_mfma_f32_16x16x32_bf16 v[40:43], v[150:153], v[186:189], v[40:43]
	v_mfma_f32_16x16x32_bf16 v[36:39], v[158:161], v[186:189], v[36:39]
	v_mfma_f32_16x16x32_bf16 v[32:35], v[134:137], v[194:197], v[32:35]
	v_mfma_f32_16x16x32_bf16 v[28:31], v[142:145], v[194:197], v[28:31]
	v_mfma_f32_16x16x32_bf16 v[24:27], v[150:153], v[194:197], v[24:27]
	v_mfma_f32_16x16x32_bf16 v[20:23], v[158:161], v[194:197], v[20:23]
	v_mfma_f32_16x16x32_bf16 v[16:19], v[134:137], v[202:205], v[16:19]
	v_mfma_f32_16x16x32_bf16 v[12:15], v[142:145], v[202:205], v[12:15]
	v_mfma_f32_16x16x32_bf16 v[8:11], v[150:153], v[202:205], v[8:11]
	v_mfma_f32_16x16x32_bf16 v[4:7], v[158:161], v[202:205], v[4:7]
	s_setprio 0
	s_setprio 1
	v_mfma_f32_16x16x32_bf16 v[64:67], v[138:141], v[180:183], v[64:67]
	v_mfma_f32_16x16x32_bf16 v[60:63], v[146:149], v[180:183], v[60:63]
	v_mfma_f32_16x16x32_bf16 v[56:59], v[154:157], v[180:183], v[56:59]
	v_mfma_f32_16x16x32_bf16 v[52:55], v[172:175], v[180:183], v[52:55]
	v_mfma_f32_16x16x32_bf16 v[48:51], v[138:141], v[190:193], v[48:51]
	v_mfma_f32_16x16x32_bf16 v[44:47], v[146:149], v[190:193], v[44:47]
	v_mfma_f32_16x16x32_bf16 v[40:43], v[154:157], v[190:193], v[40:43]
	v_mfma_f32_16x16x32_bf16 v[36:39], v[172:175], v[190:193], v[36:39]
	v_mfma_f32_16x16x32_bf16 v[32:35], v[138:141], v[198:201], v[32:35]
	v_mfma_f32_16x16x32_bf16 v[28:31], v[146:149], v[198:201], v[28:31]
	v_mfma_f32_16x16x32_bf16 v[24:27], v[154:157], v[198:201], v[24:27]
	v_mfma_f32_16x16x32_bf16 v[20:23], v[172:175], v[198:201], v[20:23]
	v_mfma_f32_16x16x32_bf16 v[16:19], v[138:141], v[206:209], v[16:19]
	v_mfma_f32_16x16x32_bf16 v[12:15], v[146:149], v[206:209], v[12:15]
	v_mfma_f32_16x16x32_bf16 v[8:11], v[154:157], v[206:209], v[8:11]
	v_mfma_f32_16x16x32_bf16 v[4:7], v[172:175], v[206:209], v[4:7]
	s_setprio 0
	s_barrier
	s_add_i32 s75, s75, 2
	s_add_u32 s55, s55, 0x100
	s_addc_u32 s74, s74, 0
	s_cmpk_gt_u32 s75, 0x55
	s_mov_b64 s[16:17], s[18:19]
	s_cbranch_scc1 .LBB0_45

; #define PG8_STAGE(bufoff, gbase, voff) do { _Pragma("unroll") for (int _i = 0; _i < 2; ++_i) \
;         __builtin_amdgcn_global_load_lds((const unsigned*)((const char*)(gbase) + (voff)[_i]), (PG8_LAS unsigned*)(lds + (bufoff) + ldsw + _i * 8192), 16, 0, 0); } while (0)
; #define PG8_LDA(dst, b, h) do { _Pragma("unroll") for (int m = 0; m < 4; ++m) _Pragma("unroll") for (int k = 0; k < 2; ++k) dst[m][k] = *(const PG8_LAS bf16x8*)(lds + PG8_SA(b, h) + aoff + m * 2048 + k * 1024); } while (0)
; #define PG8_LDB(dst, b, h) do { _Pragma("unroll") for (int n = 0; n < 2; ++n) _Pragma("unroll") for (int k = 0; k < 2; ++k) dst[n][k] = *(const PG8_LAS bf16x8*)(lds + PG8_SB(b, h) + boff + n * 2048 + k * 1024); } while (0)
; #define PG8_MMA(ai, bj, At, Bt) do { __builtin_amdgcn_s_setprio(1); _Pragma("unroll") for (int m = 0; m < 4; ++m) _Pragma("unroll") for (int n = 0; n < 2; ++n) _Pragma("unroll") for (int k = 0; k < 2; ++k) \
;         acc[ai][bj][m][n] = __builtin_amdgcn_mfma_f32_16x16x32_bf16(Bt[n][k], At[m][k], acc[ai][bj][m][n], 0, 0, 0); __builtin_amdgcn_s_setprio(0); } while (0)
; #define PG8_WAIT_V(n) asm volatile("s_waitcnt vmcnt(" #n ")" ::: "memory")
; #define PG8_BAR __builtin_amdgcn_s_barrier()
; template <class Epi, class Sched, bool ALIGN_EPI = false, bool SP2 = false>
; __device__ __forceinline__ void gemm_phase(PG8_LAS unsigned char* lds, const Gemm g, const Sched& S, const Epi& E, const int tid) {
;     ...
;             const char* a1 = cA + (size_t)(t + 1) * kstep;
;             const char* a2 = last ? nA : cA + (size_t)(t + 2) * kstep; const char* b2 = last ? nB : cB + (size_t)(t + 2) * kstep;
;             const char* a3 = a2 + kstep; const char* b3 = b2 + kstep;
;             if (last && has_next) S.a_ready(nxt);
;             if (last) E.prefetch(lds + EPI_LDS_OFF + wid * 1024, cur, wr, wc, lane);
;             if constexpr (SP2) {
;             PG8_LDB(B0, 0, 0); PG8_LDB(B1, 0, 1); PG8_SCHED; PG8_LDA(At, 0, 0); PG8_STAGE(PG8_SA(1, 1), a1 + hstep, voffA);
;             PG8_WAIT_V(8); PG8_WAIT_L(0); PG8_BAR; PG8_MMA(0, 0, At, B0); PG8_MMA(0, 1, At, B1); PG8_BAR; PG8_SCHED;
;             PG8_LDA(At, 0, 1); PG8_STAGE(PG8_SB(0, 0), b2, voffB); PG8_STAGE(PG8_SB(0, 1), b2 + hstep, voffB); PG8_STAGE(PG8_SA(0, 0), a2, voffA);
;             PG8_WAIT_V(8); PG8_WAIT_L(0); PG8_BAR; PG8_MMA(1, 0, At, B0); PG8_MMA(1, 1, At, B1); PG8_BAR; PG8_SCHED;
.LBB0_74:
	s_add_u32 s30, s24, 0xfff80080
	s_addc_u32 s31, s25, -1
	s_and_b64 s[28:29], s[28:29], exec
	s_cselect_b32 s31, s17, s31
	s_cselect_b32 s30, s23, s30
	s_cselect_b32 s29, s99, s50
	s_cselect_b32 s28, vcc_lo, vcc_hi
	s_add_i32 s42, 0, 0x10000
	v_add_u32_e32 v110, s42, v247
	s_add_i32 s3, 0, 0x14000
	ds_read_b128 v[98:101], v110
	ds_read_b128 v[102:105], v110 offset:1024
	ds_read_b128 v[106:109], v110 offset:2048
	ds_read_b128 v[144:147], v110 offset:3072
	v_add_u32_e32 v110, s3, v247
	ds_read_b128 v[152:155], v110
	ds_read_b128 v[156:159], v110 offset:1024
	ds_read_b128 v[160:163], v110 offset:2048
	ds_read_b128 v[164:167], v110 offset:3072
	v_lshl_add_u64 v[110:111], s[24:25], 0, v[190:191]
	s_add_i32 m0, s49, 0xc000
	ds_read_b128 v[168:171], v253
	ds_read_b128 v[172:175], v253 offset:1024
	ds_read_b128 v[176:179], v253 offset:2048
	ds_read_b128 v[194:197], v253 offset:3072
	ds_read_b128 v[198:201], v253 offset:4096
	ds_read_b128 v[202:205], v253 offset:5120
	ds_read_b128 v[206:209], v253 offset:6144
	ds_read_b128 v[210:213], v253 offset:7168
	global_load_lds_dwordx4 v[110:111], off
	v_lshl_add_u64 v[110:111], s[24:25], 0, v[192:193]
	s_add_i32 m0, s49, 0xe000
	s_nop 0
	global_load_lds_dwordx4 v[110:111], off
	s_waitcnt vmcnt(8)
	s_waitcnt lgkmcnt(0)
	s_setprio 1
	s_barrier
	v_mfma_f32_16x16x32_bf16 v[148:151], v[98:101], v[168:171], v[148:151]
	v_mfma_f32_16x16x32_bf16 v[140:143], v[106:109], v[168:171], v[140:143]
	v_mfma_f32_16x16x32_bf16 v[128:131], v[98:101], v[176:179], v[128:131]
	v_mfma_f32_16x16x32_bf16 v[124:127], v[106:109], v[176:179], v[124:127]
	v_mfma_f32_16x16x32_bf16 v[110:113], v[98:101], v[198:201], v[112:115]
	v_mfma_f32_16x16x32_bf16 v[92:95], v[106:109], v[198:201], v[92:95]
	v_mfma_f32_16x16x32_bf16 v[80:83], v[98:101], v[206:209], v[80:83]
	v_mfma_f32_16x16x32_bf16 v[76:79], v[106:109], v[206:209], v[76:79]
	v_mfma_f32_16x16x32_bf16 v[148:151], v[102:105], v[172:175], v[148:151]
	v_mfma_f32_16x16x32_bf16 v[140:143], v[144:147], v[172:175], v[140:143]
	v_mfma_f32_16x16x32_bf16 v[128:131], v[102:105], v[194:197], v[128:131]
	v_mfma_f32_16x16x32_bf16 v[124:127], v[144:147], v[194:197], v[124:127]
	v_mfma_f32_16x16x32_bf16 v[110:113], v[102:105], v[202:205], v[110:113]
	v_mfma_f32_16x16x32_bf16 v[92:95], v[144:147], v[202:205], v[92:95]
	v_mfma_f32_16x16x32_bf16 v[80:83], v[102:105], v[210:213], v[80:83]
	v_mfma_f32_16x16x32_bf16 v[76:79], v[144:147], v[210:213], v[76:79]
	s_setprio 0
	s_setprio 1
	v_mfma_f32_16x16x32_bf16 v[136:139], v[152:155], v[168:171], v[136:139]
	v_mfma_f32_16x16x32_bf16 v[132:135], v[160:163], v[168:171], v[132:135]
	v_mfma_f32_16x16x32_bf16 v[120:123], v[152:155], v[176:179], v[120:123]
	v_mfma_f32_16x16x32_bf16 v[114:117], v[160:163], v[176:179], v[116:119]
	v_mfma_f32_16x16x32_bf16 v[88:91], v[152:155], v[198:201], v[88:91]
	v_mfma_f32_16x16x32_bf16 v[84:87], v[160:163], v[198:201], v[84:87]
	v_mfma_f32_16x16x32_bf16 v[72:75], v[152:155], v[206:209], v[72:75]
	v_mfma_f32_16x16x32_bf16 v[68:71], v[160:163], v[206:209], v[68:71]
	v_mfma_f32_16x16x32_bf16 v[136:139], v[156:159], v[172:175], v[136:139]
	v_mfma_f32_16x16x32_bf16 v[132:135], v[164:167], v[172:175], v[132:135]
	v_mfma_f32_16x16x32_bf16 v[120:123], v[156:159], v[194:197], v[120:123]
	v_mfma_f32_16x16x32_bf16 v[116:119], v[164:167], v[194:197], v[114:117]
	v_mfma_f32_16x16x32_bf16 v[88:91], v[156:159], v[202:205], v[88:91]
	v_mfma_f32_16x16x32_bf16 v[84:87], v[164:167], v[202:205], v[84:87]
	v_mfma_f32_16x16x32_bf16 v[72:75], v[156:159], v[210:213], v[72:75]
	v_mfma_f32_16x16x32_bf16 v[68:71], v[164:167], v[210:213], v[68:71]
	s_setprio 0
	s_barrier
	s_add_i32 s42, s42, s48
	v_lshl_add_u64 v[180:181], s[28:29], 0, v[2:3]
	s_mov_b32 m0, s42
	ds_read_b128 v[168:171], v253 offset:16384
	ds_read_b128 v[172:175], v253 offset:17408
	ds_read_b128 v[176:179], v253 offset:18432
	ds_read_b128 v[194:197], v253 offset:19456
	ds_read_b128 v[198:201], v253 offset:20480
	ds_read_b128 v[202:205], v253 offset:21504
	ds_read_b128 v[206:209], v253 offset:22528
	ds_read_b128 v[210:213], v253 offset:23552
	global_load_lds_dwordx4 v[180:181], off
	s_add_i32 m0, s42, 0x2000
	s_add_u32 s42, s28, 0x80000
	v_lshl_add_u64 v[182:183], s[28:29], 0, v[188:189]
	s_addc_u32 s43, s29, 0
	s_add_i32 s3, s3, s48
	global_load_lds_dwordx4 v[182:183], off
	v_lshl_add_u64 v[114:115], s[42:43], 0, v[2:3]
	s_mov_b32 m0, s3
	v_lshl_add_u64 v[214:215], s[30:31], 0, v[0:1]
	global_load_lds_dwordx4 v[114:115], off
	v_lshl_add_u64 v[114:115], s[42:43], 0, v[188:189]
	s_add_i32 m0, s3, 0x2000
	v_lshl_add_u64 v[216:217], s[30:31], 0, v[186:187]
	global_load_lds_dwordx4 v[114:115], off
	s_mov_b32 m0, s49
	s_nop 0
	global_load_lds_dwordx4 v[214:215], off
	s_mov_b32 m0, s52
	s_nop 0
	global_load_lds_dwordx4 v[216:217], off
	s_waitcnt vmcnt(8)
	s_waitcnt lgkmcnt(0)
	s_setprio 1
	s_barrier
; #define PG8_STAGE(bufoff, gbase, voff) do { _Pragma("unroll") for (int _i = 0; _i < 2; ++_i) \
;         __builtin_amdgcn_global_load_lds((const unsigned*)((const char*)(gbase) + (voff)[_i]), (PG8_LAS unsigned*)(lds + (bufoff) + ldsw + _i * 8192), 16, 0, 0); } while (0)
; #define PG8_LDA(dst, b, h) do { _Pragma("unroll") for (int m = 0; m < 4; ++m) _Pragma("unroll") for (int k = 0; k < 2; ++k) dst[m][k] = *(const PG8_LAS bf16x8*)(lds + PG8_SA(b, h) + aoff + m * 2048 + k * 1024); } while (0)
; #define PG8_LDB(dst, b, h) do { _Pragma("unroll") for (int n = 0; n < 2; ++n) _Pragma("unroll") for (int k = 0; k < 2; ++k) dst[n][k] = *(const PG8_LAS bf16x8*)(lds + PG8_SB(b, h) + boff + n * 2048 + k * 1024); } while (0)
; #define PG8_MMA(ai, bj, At, Bt) do { __builtin_amdgcn_s_setprio(1); _Pragma("unroll") for (int m = 0; m < 4; ++m) _Pragma("unroll") for (int n = 0; n < 2; ++n) _Pragma("unroll") for (int k = 0; k < 2; ++k) \
;         acc[ai][bj][m][n] = __builtin_amdgcn_mfma_f32_16x16x32_bf16(Bt[n][k], At[m][k], acc[ai][bj][m][n], 0, 0, 0); __builtin_amdgcn_s_setprio(0); } while (0)
; #define PG8_WAIT_V(n) asm volatile("s_waitcnt vmcnt(" #n ")" ::: "memory")
; #define PG8_WAIT_L(n) asm volatile("s_waitcnt lgkmcnt(" #n ")" ::: "memory")
; #define PG8_BAR __builtin_amdgcn_s_barrier()
; #define PG8_SCHED __builtin_amdgcn_sched_barrier(0)
; template <class Epi, class Sched, bool ALIGN_EPI = false, bool SP2 = false>
; __device__ __forceinline__ void gemm_phase(PG8_LAS unsigned char* lds, const Gemm g, const Sched& S, const Epi& E, const int tid) {
;     ...
;             PG8_WAIT_V(8); PG8_WAIT_L(0); PG8_BAR; PG8_MMA(1, 0, At, B0); PG8_MMA(1, 1, At, B1); PG8_BAR; PG8_SCHED;
;             PG8_LDB(B0, 1, 0); PG8_LDB(B1, 1, 1); PG8_SCHED; PG8_LDA(At, 1, 0); PG8_STAGE(PG8_SA(0, 1), a2 + hstep, voffA);
;             PG8_WAIT_V(8); PG8_WAIT_L(0); PG8_BAR; PG8_MMA(0, 0, At, B0); PG8_MMA(0, 1, At, B1); PG8_BAR; PG8_SCHED;
	v_mfma_f32_16x16x32_bf16 v[64:67], v[98:101], v[168:171], v[64:67]
	v_mfma_f32_16x16x32_bf16 v[60:63], v[106:109], v[168:171], v[60:63]
	v_mfma_f32_16x16x32_bf16 v[56:59], v[152:155], v[168:171], v[56:59]
	v_mfma_f32_16x16x32_bf16 v[52:55], v[160:163], v[168:171], v[52:55]
	v_mfma_f32_16x16x32_bf16 v[48:51], v[98:101], v[176:179], v[48:51]
	v_mfma_f32_16x16x32_bf16 v[44:47], v[106:109], v[176:179], v[44:47]
	v_mfma_f32_16x16x32_bf16 v[40:43], v[152:155], v[176:179], v[40:43]
	v_mfma_f32_16x16x32_bf16 v[36:39], v[160:163], v[176:179], v[36:39]
	v_mfma_f32_16x16x32_bf16 v[32:35], v[98:101], v[198:201], v[32:35]
	v_mfma_f32_16x16x32_bf16 v[28:31], v[106:109], v[198:201], v[28:31]
	v_mfma_f32_16x16x32_bf16 v[24:27], v[152:155], v[198:201], v[24:27]
	v_mfma_f32_16x16x32_bf16 v[20:23], v[160:163], v[198:201], v[20:23]
	v_mfma_f32_16x16x32_bf16 v[16:19], v[98:101], v[206:209], v[16:19]
	v_mfma_f32_16x16x32_bf16 v[12:15], v[106:109], v[206:209], v[12:15]
	v_mfma_f32_16x16x32_bf16 v[8:11], v[152:155], v[206:209], v[8:11]
	v_mfma_f32_16x16x32_bf16 v[4:7], v[160:163], v[206:209], v[4:7]
	s_setprio 0
	s_setprio 1
	v_mfma_f32_16x16x32_bf16 v[64:67], v[102:105], v[172:175], v[64:67]
	v_mfma_f32_16x16x32_bf16 v[60:63], v[144:147], v[172:175], v[60:63]
	v_mfma_f32_16x16x32_bf16 v[56:59], v[156:159], v[172:175], v[56:59]
	v_mfma_f32_16x16x32_bf16 v[52:55], v[164:167], v[172:175], v[52:55]
	v_mfma_f32_16x16x32_bf16 v[48:51], v[102:105], v[194:197], v[48:51]
	v_mfma_f32_16x16x32_bf16 v[44:47], v[144:147], v[194:197], v[44:47]
	v_mfma_f32_16x16x32_bf16 v[40:43], v[156:159], v[194:197], v[40:43]
	v_mfma_f32_16x16x32_bf16 v[36:39], v[164:167], v[194:197], v[36:39]
	v_mfma_f32_16x16x32_bf16 v[32:35], v[102:105], v[202:205], v[32:35]
	v_mfma_f32_16x16x32_bf16 v[28:31], v[144:147], v[202:205], v[28:31]
	v_mfma_f32_16x16x32_bf16 v[24:27], v[156:159], v[202:205], v[24:27]
	v_mfma_f32_16x16x32_bf16 v[20:23], v[164:167], v[202:205], v[20:23]
	v_mfma_f32_16x16x32_bf16 v[16:19], v[102:105], v[210:213], v[16:19]
	v_mfma_f32_16x16x32_bf16 v[12:15], v[144:147], v[210:213], v[12:15]
	v_mfma_f32_16x16x32_bf16 v[8:11], v[156:159], v[210:213], v[8:11]
	v_mfma_f32_16x16x32_bf16 v[4:7], v[164:167], v[210:213], v[4:7]
	s_setprio 0
	s_barrier
	s_add_i32 s3, 0, 0x18000
	v_add_u32_e32 v114, s3, v247
	s_add_i32 s42, 0, 0x1c000
	ds_read_b128 v[98:101], v114
	ds_read_b128 v[102:105], v114 offset:1024
	ds_read_b128 v[106:109], v114 offset:2048
	ds_read_b128 v[144:147], v114 offset:3072
	v_add_u32_e32 v114, s42, v247
	ds_read_b128 v[152:155], v114
	ds_read_b128 v[156:159], v114 offset:1024
	ds_read_b128 v[160:163], v114 offset:2048
	ds_read_b128 v[164:167], v114 offset:3072
	s_add_u32 s30, s30, 0x80000
	s_addc_u32 s31, s31, 0
	s_mov_b32 m0, s53
	v_lshl_add_u64 v[114:115], s[30:31], 0, v[0:1]
	ds_read_b128 v[168:171], v253 offset:32768
	ds_read_b128 v[172:175], v253 offset:33792
	ds_read_b128 v[176:179], v253 offset:34816
	ds_read_b128 v[194:197], v253 offset:35840
	ds_read_b128 v[198:201], v253 offset:36864
	ds_read_b128 v[202:205], v253 offset:37888
	ds_read_b128 v[206:209], v253 offset:38912
	ds_read_b128 v[210:213], v253 offset:39936
	global_load_lds_dwordx4 v[114:115], off
	v_lshl_add_u64 v[114:115], s[30:31], 0, v[186:187]
	s_mov_b32 m0, s54
	s_nop 0
	global_load_lds_dwordx4 v[114:115], off
	s_waitcnt vmcnt(8)
	s_waitcnt lgkmcnt(0)
	s_setprio 1
	s_barrier
	v_mfma_f32_16x16x32_bf16 v[148:151], v[98:101], v[168:171], v[148:151]
	v_mfma_f32_16x16x32_bf16 v[140:143], v[106:109], v[168:171], v[140:143]
	v_mfma_f32_16x16x32_bf16 v[128:131], v[98:101], v[176:179], v[128:131]
	v_mfma_f32_16x16x32_bf16 v[124:127], v[106:109], v[176:179], v[124:127]
	v_mfma_f32_16x16x32_bf16 v[110:113], v[98:101], v[198:201], v[110:113]
	v_mfma_f32_16x16x32_bf16 v[92:95], v[106:109], v[198:201], v[92:95]
	v_mfma_f32_16x16x32_bf16 v[80:83], v[98:101], v[206:209], v[80:83]
	v_mfma_f32_16x16x32_bf16 v[76:79], v[106:109], v[206:209], v[76:79]
	v_mfma_f32_16x16x32_bf16 v[148:151], v[102:105], v[172:175], v[148:151]
	v_mfma_f32_16x16x32_bf16 v[140:143], v[144:147], v[172:175], v[140:143]
	v_mfma_f32_16x16x32_bf16 v[128:131], v[102:105], v[194:197], v[128:131]
	v_mfma_f32_16x16x32_bf16 v[124:127], v[144:147], v[194:197], v[124:127]
	v_mfma_f32_16x16x32_bf16 v[112:115], v[102:105], v[202:205], v[110:113]
	v_mfma_f32_16x16x32_bf16 v[92:95], v[144:147], v[202:205], v[92:95]
	v_mfma_f32_16x16x32_bf16 v[80:83], v[102:105], v[210:213], v[80:83]
	v_mfma_f32_16x16x32_bf16 v[76:79], v[144:147], v[210:213], v[76:79]
	s_setprio 0
	s_setprio 1
	v_mfma_f32_16x16x32_bf16 v[136:139], v[152:155], v[168:171], v[136:139]
	v_mfma_f32_16x16x32_bf16 v[132:135], v[160:163], v[168:171], v[132:135]
	v_mfma_f32_16x16x32_bf16 v[120:123], v[152:155], v[176:179], v[120:123]
	v_mfma_f32_16x16x32_bf16 v[116:119], v[160:163], v[176:179], v[116:119]
	v_mfma_f32_16x16x32_bf16 v[88:91], v[152:155], v[198:201], v[88:91]
	v_mfma_f32_16x16x32_bf16 v[84:87], v[160:163], v[198:201], v[84:87]
	v_mfma_f32_16x16x32_bf16 v[72:75], v[152:155], v[206:209], v[72:75]
	v_mfma_f32_16x16x32_bf16 v[68:71], v[160:163], v[206:209], v[68:71]
	v_mfma_f32_16x16x32_bf16 v[136:139], v[156:159], v[172:175], v[136:139]
	v_mfma_f32_16x16x32_bf16 v[132:135], v[164:167], v[172:175], v[132:135]
	v_mfma_f32_16x16x32_bf16 v[120:123], v[156:159], v[194:197], v[120:123]
	v_mfma_f32_16x16x32_bf16 v[116:119], v[164:167], v[194:197], v[116:119]
	v_mfma_f32_16x16x32_bf16 v[88:91], v[156:159], v[202:205], v[88:91]
	v_mfma_f32_16x16x32_bf16 v[84:87], v[164:167], v[202:205], v[84:87]
	v_mfma_f32_16x16x32_bf16 v[72:75], v[156:159], v[210:213], v[72:75]
	v_mfma_f32_16x16x32_bf16 v[68:71], v[164:167], v[210:213], v[68:71]
	s_setprio 0
	s_barrier
; #define PG8_STAGE(bufoff, gbase, voff) do { _Pragma("unroll") for (int _i = 0; _i < 2; ++_i) \
;         __builtin_amdgcn_global_load_lds((const unsigned*)((const char*)(gbase) + (voff)[_i]), (PG8_LAS unsigned*)(lds + (bufoff) + ldsw + _i * 8192), 16, 0, 0); } while (0)
; #define PG8_LDA(dst, b, h) do { _Pragma("unroll") for (int m = 0; m < 4; ++m) _Pragma("unroll") for (int k = 0; k < 2; ++k) dst[m][k] = *(const PG8_LAS bf16x8*)(lds + PG8_SA(b, h) + aoff + m * 2048 + k * 1024); } while (0)
; #define PG8_MMA(ai, bj, At, Bt) do { __builtin_amdgcn_s_setprio(1); _Pragma("unroll") for (int m = 0; m < 4; ++m) _Pragma("unroll") for (int n = 0; n < 2; ++n) _Pragma("unroll") for (int k = 0; k < 2; ++k) \
;         acc[ai][bj][m][n] = __builtin_amdgcn_mfma_f32_16x16x32_bf16(Bt[n][k], At[m][k], acc[ai][bj][m][n], 0, 0, 0); __builtin_amdgcn_s_setprio(0); } while (0)
; #define PG8_WAIT_V(n) asm volatile("s_waitcnt vmcnt(" #n ")" ::: "memory")
; #define PG8_WAIT_L(n) asm volatile("s_waitcnt lgkmcnt(" #n ")" ::: "memory")
; #define PG8_BAR __builtin_amdgcn_s_barrier()
; #define PG8_SCHED __builtin_amdgcn_sched_barrier(0)
; template <class Epi, class Sched, bool ALIGN_EPI = false, bool SP2 = false>
; __device__ __forceinline__ void gemm_phase(PG8_LAS unsigned char* lds, const Gemm g, const Sched& S, const Epi& E, const int tid) {
;     ...
;             PG8_LDA(At, 1, 1); PG8_STAGE(PG8_SB(1, 0), b3, voffB); PG8_STAGE(PG8_SB(1, 1), b3 + hstep, voffB); PG8_STAGE(PG8_SA(1, 0), a3, voffA);
;             PG8_WAIT_V(8); PG8_WAIT_L(0); PG8_BAR; PG8_MMA(1, 0, At, B0); PG8_MMA(1, 1, At, B1); PG8_BAR; PG8_SCHED;
	s_add_i32 s3, s3, s48
	v_lshl_add_u64 v[110:111], v[180:181], 0, s[46:47]
	s_mov_b32 m0, s3
	ds_read_b128 v[168:171], v253 offset:49152
	ds_read_b128 v[172:175], v253 offset:50176
	ds_read_b128 v[176:179], v253 offset:51200
	ds_read_b128 v[194:197], v253 offset:52224
	ds_read_b128 v[198:201], v253 offset:53248
	ds_read_b128 v[202:205], v253 offset:54272
	ds_read_b128 v[206:209], v253 offset:55296
	ds_read_b128 v[210:213], v253 offset:56320
	global_load_lds_dwordx4 v[110:111], off
	s_add_i32 m0, s3, 0x2000
	s_add_u32 s28, s28, 0x80080
	v_lshl_add_u64 v[110:111], v[182:183], 0, s[46:47]
	s_addc_u32 s29, s29, 0
	s_add_i32 s3, s42, s48
	global_load_lds_dwordx4 v[110:111], off
	v_lshl_add_u64 v[110:111], s[28:29], 0, v[2:3]
	s_mov_b32 m0, s3
	s_nop 0
	global_load_lds_dwordx4 v[110:111], off
	v_lshl_add_u64 v[110:111], s[28:29], 0, v[188:189]
	s_add_i32 m0, s3, 0x2000
	s_nop 0
	global_load_lds_dwordx4 v[110:111], off
	v_lshl_add_u64 v[110:111], v[214:215], 0, s[46:47]
	s_mov_b32 m0, s55
	s_nop 0
	global_load_lds_dwordx4 v[110:111], off
	v_lshl_add_u64 v[110:111], v[216:217], 0, s[46:47]
	s_mov_b32 m0, s74
	s_nop 0
	global_load_lds_dwordx4 v[110:111], off
	s_waitcnt vmcnt(8)
	s_waitcnt lgkmcnt(0)
	s_setprio 1
	s_barrier
	v_mfma_f32_16x16x32_bf16 v[64:67], v[98:101], v[168:171], v[64:67]
	v_mfma_f32_16x16x32_bf16 v[60:63], v[106:109], v[168:171], v[60:63]
	v_mfma_f32_16x16x32_bf16 v[56:59], v[152:155], v[168:171], v[56:59]
	v_mfma_f32_16x16x32_bf16 v[52:55], v[160:163], v[168:171], v[52:55]
	v_mfma_f32_16x16x32_bf16 v[48:51], v[98:101], v[176:179], v[48:51]
	v_mfma_f32_16x16x32_bf16 v[44:47], v[106:109], v[176:179], v[44:47]
	v_mfma_f32_16x16x32_bf16 v[40:43], v[152:155], v[176:179], v[40:43]
	v_mfma_f32_16x16x32_bf16 v[36:39], v[160:163], v[176:179], v[36:39]
	v_mfma_f32_16x16x32_bf16 v[32:35], v[98:101], v[198:201], v[32:35]
	v_mfma_f32_16x16x32_bf16 v[28:31], v[106:109], v[198:201], v[28:31]
	v_mfma_f32_16x16x32_bf16 v[24:27], v[152:155], v[198:201], v[24:27]
	v_mfma_f32_16x16x32_bf16 v[20:23], v[160:163], v[198:201], v[20:23]
	v_mfma_f32_16x16x32_bf16 v[16:19], v[98:101], v[206:209], v[16:19]
	v_mfma_f32_16x16x32_bf16 v[12:15], v[106:109], v[206:209], v[12:15]
	v_mfma_f32_16x16x32_bf16 v[8:11], v[152:155], v[206:209], v[8:11]
	v_mfma_f32_16x16x32_bf16 v[4:7], v[160:163], v[206:209], v[4:7]
	s_setprio 0
	s_setprio 1
	v_mfma_f32_16x16x32_bf16 v[64:67], v[102:105], v[172:175], v[64:67]
	v_mfma_f32_16x16x32_bf16 v[60:63], v[144:147], v[172:175], v[60:63]
	v_mfma_f32_16x16x32_bf16 v[56:59], v[156:159], v[172:175], v[56:59]
	v_mfma_f32_16x16x32_bf16 v[52:55], v[164:167], v[172:175], v[52:55]
	v_mfma_f32_16x16x32_bf16 v[48:51], v[102:105], v[194:197], v[48:51]
	v_mfma_f32_16x16x32_bf16 v[44:47], v[144:147], v[194:197], v[44:47]
	v_mfma_f32_16x16x32_bf16 v[40:43], v[156:159], v[194:197], v[40:43]
	v_mfma_f32_16x16x32_bf16 v[36:39], v[164:167], v[194:197], v[36:39]
	v_mfma_f32_16x16x32_bf16 v[32:35], v[102:105], v[202:205], v[32:35]
	v_mfma_f32_16x16x32_bf16 v[28:31], v[144:147], v[202:205], v[28:31]
	v_mfma_f32_16x16x32_bf16 v[24:27], v[156:159], v[202:205], v[24:27]
	v_mfma_f32_16x16x32_bf16 v[20:23], v[164:167], v[202:205], v[20:23]
	v_mfma_f32_16x16x32_bf16 v[16:19], v[102:105], v[210:213], v[16:19]
	v_mfma_f32_16x16x32_bf16 v[12:15], v[144:147], v[210:213], v[12:15]
	v_mfma_f32_16x16x32_bf16 v[8:11], v[156:159], v[210:213], v[8:11]
	v_mfma_f32_16x16x32_bf16 v[4:7], v[164:167], v[210:213], v[4:7]
	s_setprio 0
	s_barrier
	s_add_i32 s51, s51, 2
	s_add_u32 s24, s24, 0x100
	s_addc_u32 s25, s25, 0
	s_add_u32 vcc_hi, vcc_hi, 0x100
	s_addc_u32 s50, s50, 0
	s_cmp_gt_u32 s51, 29
	s_cbranch_scc1 .LBB0_77

; #define PG8_STAGE(bufoff, gbase, voff) do { _Pragma("unroll") for (int _i = 0; _i < 2; ++_i) \
;         __builtin_amdgcn_global_load_lds((const unsigned*)((const char*)(gbase) + (voff)[_i]), (PG8_LAS unsigned*)(lds + (bufoff) + ldsw + _i * 8192), 16, 0, 0); } while (0)
; #define PG8_LDA(dst, b, h) do { _Pragma("unroll") for (int m = 0; m < 4; ++m) _Pragma("unroll") for (int k = 0; k < 2; ++k) dst[m][k] = *(const PG8_LAS bf16x8*)(lds + PG8_SA(b, h) + aoff + m * 2048 + k * 1024); } while (0)
; #define PG8_LDB(dst, b, h) do { _Pragma("unroll") for (int n = 0; n < 2; ++n) _Pragma("unroll") for (int k = 0; k < 2; ++k) dst[n][k] = *(const PG8_LAS bf16x8*)(lds + PG8_SB(b, h) + boff + n * 2048 + k * 1024); } while (0)
; #define PG8_MMA(ai, bj, At, Bt) do { __builtin_amdgcn_s_setprio(1); _Pragma("unroll") for (int m = 0; m < 4; ++m) _Pragma("unroll") for (int n = 0; n < 2; ++n) _Pragma("unroll") for (int k = 0; k < 2; ++k) \
;         acc[ai][bj][m][n] = __builtin_amdgcn_mfma_f32_16x16x32_bf16(Bt[n][k], At[m][k], acc[ai][bj][m][n], 0, 0, 0); __builtin_amdgcn_s_setprio(0); } while (0)
; #define PG8_WAIT_V(n) asm volatile("s_waitcnt vmcnt(" #n ")" ::: "memory")
; #define PG8_BAR __builtin_amdgcn_s_barrier()
; template <class Epi, class Sched, bool ALIGN_EPI = false, bool SP2 = false>
; __device__ __forceinline__ void gemm_phase(PG8_LAS unsigned char* lds, const Gemm g, const Sched& S, const Epi& E, const int tid) {
;     ...
;             const char* a1 = cA + (size_t)(t + 1) * kstep;
;             const char* a2 = last ? nA : cA + (size_t)(t + 2) * kstep; const char* b2 = last ? nB : cB + (size_t)(t + 2) * kstep;
;             const char* a3 = a2 + kstep; const char* b3 = b2 + kstep;
;             if (last && has_next) S.a_ready(nxt);
;             if (last) E.prefetch(lds + EPI_LDS_OFF + wid * 1024, cur, wr, wc, lane);
;             if constexpr (SP2) {
;             PG8_LDB(B0, 0, 0); PG8_LDB(B1, 0, 1); PG8_SCHED; PG8_LDA(At, 0, 0); PG8_STAGE(PG8_SA(1, 1), a1 + hstep, voffA);
;             PG8_WAIT_V(8); PG8_WAIT_L(0); PG8_BAR; PG8_MMA(0, 0, At, B0); PG8_MMA(0, 1, At, B1); PG8_BAR; PG8_SCHED;
;             PG8_LDA(At, 0, 1); PG8_STAGE(PG8_SB(0, 0), b2, voffB); PG8_STAGE(PG8_SB(0, 1), b2 + hstep, voffB); PG8_STAGE(PG8_SA(0, 0), a2, voffA);
;             PG8_WAIT_V(8); PG8_WAIT_L(0); PG8_BAR; PG8_MMA(1, 0, At, B0); PG8_MMA(1, 1, At, B1); PG8_BAR; PG8_SCHED;
.LBB0_156:
	s_add_u32 s3, s26, 0xfff80080
	s_addc_u32 s30, s27, -1
	s_and_b64 s[28:29], s[28:29], exec
	s_cselect_b32 s31, s9, s30
	s_cselect_b32 s30, s17, s3
	s_cselect_b32 s29, s15, s25
	s_cselect_b32 s28, s39, s23
	s_add_i32 s3, 0, 0x10000
	v_add_u32_e32 v34, s3, v167
	s_add_i32 s51, 0, 0x14000
	ds_read_b128 v[44:47], v34
	ds_read_b128 v[48:51], v34 offset:1024
	ds_read_b128 v[160:163], v34 offset:2048
	ds_read_b128 v[172:175], v34 offset:3072
	v_add_u32_e32 v34, s51, v167
	ds_read_b128 v[176:179], v34
	ds_read_b128 v[180:183], v34 offset:1024
	ds_read_b128 v[186:189], v34 offset:2048
	ds_read_b128 v[190:193], v34 offset:3072
	v_lshl_add_u64 v[34:35], s[26:27], 0, v[156:157]
	s_add_i32 m0, s48, 0xc000
	ds_read_b128 v[194:197], v171
	ds_read_b128 v[198:201], v171 offset:1024
	ds_read_b128 v[202:205], v171 offset:2048
	ds_read_b128 v[206:209], v171 offset:3072
	ds_read_b128 v[210:213], v171 offset:4096
	ds_read_b128 v[214:217], v171 offset:5120
	ds_read_b128 v[218:221], v171 offset:6144
	ds_read_b128 v[222:225], v171 offset:7168
	global_load_lds_dwordx4 v[34:35], off
	v_lshl_add_u64 v[34:35], s[26:27], 0, v[158:159]
	s_add_i32 m0, s48, 0xe000
	s_nop 0
	global_load_lds_dwordx4 v[34:35], off
	s_waitcnt vmcnt(8)
	s_waitcnt lgkmcnt(0)
	s_setprio 1
	s_barrier
	v_mfma_f32_16x16x32_bf16 v[144:147], v[44:47], v[194:197], v[144:147]
	v_mfma_f32_16x16x32_bf16 v[140:143], v[160:163], v[194:197], v[140:143]
	v_mfma_f32_16x16x32_bf16 v[136:139], v[176:179], v[194:197], v[136:139]
	v_mfma_f32_16x16x32_bf16 v[132:135], v[186:189], v[194:197], v[132:135]
	v_mfma_f32_16x16x32_bf16 v[128:131], v[44:47], v[202:205], v[128:131]
	v_mfma_f32_16x16x32_bf16 v[124:127], v[160:163], v[202:205], v[124:127]
	v_mfma_f32_16x16x32_bf16 v[120:123], v[176:179], v[202:205], v[120:123]
	v_mfma_f32_16x16x32_bf16 v[116:119], v[186:189], v[202:205], v[116:119]
	v_mfma_f32_16x16x32_bf16 v[112:115], v[44:47], v[210:213], v[112:115]
	v_mfma_f32_16x16x32_bf16 v[108:111], v[160:163], v[210:213], v[108:111]
	v_mfma_f32_16x16x32_bf16 v[104:107], v[176:179], v[210:213], v[104:107]
	v_mfma_f32_16x16x32_bf16 v[100:103], v[186:189], v[210:213], v[100:103]
	v_mfma_f32_16x16x32_bf16 v[96:99], v[44:47], v[218:221], v[96:99]
	v_mfma_f32_16x16x32_bf16 v[92:95], v[160:163], v[218:221], v[92:95]
	v_mfma_f32_16x16x32_bf16 v[88:91], v[176:179], v[218:221], v[88:91]
	v_mfma_f32_16x16x32_bf16 v[84:87], v[186:189], v[218:221], v[84:87]
	s_setprio 0
	s_setprio 1
	v_mfma_f32_16x16x32_bf16 v[144:147], v[48:51], v[198:201], v[144:147]
	v_mfma_f32_16x16x32_bf16 v[140:143], v[172:175], v[198:201], v[140:143]
	v_mfma_f32_16x16x32_bf16 v[136:139], v[180:183], v[198:201], v[136:139]
	v_mfma_f32_16x16x32_bf16 v[132:135], v[190:193], v[198:201], v[132:135]
	v_mfma_f32_16x16x32_bf16 v[128:131], v[48:51], v[206:209], v[128:131]
	v_mfma_f32_16x16x32_bf16 v[124:127], v[172:175], v[206:209], v[124:127]
	v_mfma_f32_16x16x32_bf16 v[120:123], v[180:183], v[206:209], v[120:123]
	v_mfma_f32_16x16x32_bf16 v[116:119], v[190:193], v[206:209], v[116:119]
	v_mfma_f32_16x16x32_bf16 v[112:115], v[48:51], v[214:217], v[112:115]
	v_mfma_f32_16x16x32_bf16 v[108:111], v[172:175], v[214:217], v[108:111]
	v_mfma_f32_16x16x32_bf16 v[104:107], v[180:183], v[214:217], v[104:107]
	v_mfma_f32_16x16x32_bf16 v[100:103], v[190:193], v[214:217], v[100:103]
	v_mfma_f32_16x16x32_bf16 v[96:99], v[48:51], v[222:225], v[96:99]
	v_mfma_f32_16x16x32_bf16 v[92:95], v[172:175], v[222:225], v[92:95]
	v_mfma_f32_16x16x32_bf16 v[88:91], v[180:183], v[222:225], v[88:91]
	v_mfma_f32_16x16x32_bf16 v[84:87], v[190:193], v[222:225], v[84:87]
	s_setprio 0
	s_barrier
	s_add_i32 s3, s3, s44
	v_lshl_add_u64 v[164:165], s[28:29], 0, v[2:3]
	s_mov_b32 m0, s3
	ds_read_b128 v[194:197], v171 offset:16384
	ds_read_b128 v[198:201], v171 offset:17408
	ds_read_b128 v[202:205], v171 offset:18432
	ds_read_b128 v[206:209], v171 offset:19456
	ds_read_b128 v[210:213], v171 offset:20480
	ds_read_b128 v[214:217], v171 offset:21504
	ds_read_b128 v[218:221], v171 offset:22528
	ds_read_b128 v[222:225], v171 offset:23552
	global_load_lds_dwordx4 v[164:165], off
	s_add_i32 m0, s3, 0x2000
	s_add_u32 s42, s28, 0x80000
	v_lshl_add_u64 v[226:227], s[28:29], 0, v[150:151]
	s_addc_u32 s43, s29, 0
	s_add_i32 s3, s51, s44
	global_load_lds_dwordx4 v[226:227], off
	v_lshl_add_u64 v[34:35], s[42:43], 0, v[2:3]
	s_mov_b32 m0, s3
	v_lshl_add_u64 v[228:229], s[30:31], 0, v[0:1]
	global_load_lds_dwordx4 v[34:35], off
	v_lshl_add_u64 v[34:35], s[42:43], 0, v[150:151]
	s_add_i32 m0, s3, 0x2000
	v_lshl_add_u64 v[230:231], s[30:31], 0, v[148:149]
	global_load_lds_dwordx4 v[34:35], off
	s_mov_b32 m0, s48
	s_nop 0
	global_load_lds_dwordx4 v[228:229], off
	s_mov_b32 m0, s49
	s_nop 0
	global_load_lds_dwordx4 v[230:231], off
	s_waitcnt vmcnt(8)
	s_waitcnt lgkmcnt(0)
	s_setprio 1
	s_barrier
; #define PG8_STAGE(bufoff, gbase, voff) do { _Pragma("unroll") for (int _i = 0; _i < 2; ++_i) \
;         __builtin_amdgcn_global_load_lds((const unsigned*)((const char*)(gbase) + (voff)[_i]), (PG8_LAS unsigned*)(lds + (bufoff) + ldsw + _i * 8192), 16, 0, 0); } while (0)
; #define PG8_LDA(dst, b, h) do { _Pragma("unroll") for (int m = 0; m < 4; ++m) _Pragma("unroll") for (int k = 0; k < 2; ++k) dst[m][k] = *(const PG8_LAS bf16x8*)(lds + PG8_SA(b, h) + aoff + m * 2048 + k * 1024); } while (0)
; #define PG8_LDB(dst, b, h) do { _Pragma("unroll") for (int n = 0; n < 2; ++n) _Pragma("unroll") for (int k = 0; k < 2; ++k) dst[n][k] = *(const PG8_LAS bf16x8*)(lds + PG8_SB(b, h) + boff + n * 2048 + k * 1024); } while (0)
; #define PG8_MMA(ai, bj, At, Bt) do { __builtin_amdgcn_s_setprio(1); _Pragma("unroll") for (int m = 0; m < 4; ++m) _Pragma("unroll") for (int n = 0; n < 2; ++n) _Pragma("unroll") for (int k = 0; k < 2; ++k) \
;         acc[ai][bj][m][n] = __builtin_amdgcn_mfma_f32_16x16x32_bf16(Bt[n][k], At[m][k], acc[ai][bj][m][n], 0, 0, 0); __builtin_amdgcn_s_setprio(0); } while (0)
; #define PG8_WAIT_V(n) asm volatile("s_waitcnt vmcnt(" #n ")" ::: "memory")
; #define PG8_WAIT_L(n) asm volatile("s_waitcnt lgkmcnt(" #n ")" ::: "memory")
; #define PG8_BAR __builtin_amdgcn_s_barrier()
; #define PG8_SCHED __builtin_amdgcn_sched_barrier(0)
; template <class Epi, class Sched, bool ALIGN_EPI = false, bool SP2 = false>
; __device__ __forceinline__ void gemm_phase(PG8_LAS unsigned char* lds, const Gemm g, const Sched& S, const Epi& E, const int tid) {
;     ...
;             PG8_WAIT_V(8); PG8_WAIT_L(0); PG8_BAR; PG8_MMA(1, 0, At, B0); PG8_MMA(1, 1, At, B1); PG8_BAR; PG8_SCHED;
;             PG8_LDB(B0, 1, 0); PG8_LDB(B1, 1, 1); PG8_SCHED; PG8_LDA(At, 1, 0); PG8_STAGE(PG8_SA(0, 1), a2 + hstep, voffA);
;             PG8_WAIT_V(8); PG8_WAIT_L(0); PG8_BAR; PG8_MMA(0, 0, At, B0); PG8_MMA(0, 1, At, B1); PG8_BAR; PG8_SCHED;
	v_mfma_f32_16x16x32_bf16 v[80:83], v[44:47], v[194:197], v[80:83]
	v_mfma_f32_16x16x32_bf16 v[76:79], v[160:163], v[194:197], v[76:79]
	v_mfma_f32_16x16x32_bf16 v[64:67], v[44:47], v[202:205], v[64:67]
	v_mfma_f32_16x16x32_bf16 v[60:63], v[160:163], v[202:205], v[60:63]
	v_mfma_f32_16x16x32_bf16 v[40:43], v[44:47], v[210:213], v[40:43]
	v_mfma_f32_16x16x32_bf16 v[34:37], v[160:163], v[210:213], v[36:39]
	v_mfma_f32_16x16x32_bf16 v[16:19], v[44:47], v[218:221], v[16:19]
	v_mfma_f32_16x16x32_bf16 v[12:15], v[160:163], v[218:221], v[12:15]
	v_mfma_f32_16x16x32_bf16 v[80:83], v[48:51], v[198:201], v[80:83]
	v_mfma_f32_16x16x32_bf16 v[76:79], v[172:175], v[198:201], v[76:79]
	v_mfma_f32_16x16x32_bf16 v[64:67], v[48:51], v[206:209], v[64:67]
	v_mfma_f32_16x16x32_bf16 v[60:63], v[172:175], v[206:209], v[60:63]
	v_mfma_f32_16x16x32_bf16 v[40:43], v[48:51], v[214:217], v[40:43]
	v_mfma_f32_16x16x32_bf16 v[34:37], v[172:175], v[214:217], v[34:37]
	v_mfma_f32_16x16x32_bf16 v[16:19], v[48:51], v[222:225], v[16:19]
	v_mfma_f32_16x16x32_bf16 v[12:15], v[172:175], v[222:225], v[12:15]
	s_setprio 0
	s_setprio 1
	v_mfma_f32_16x16x32_bf16 v[56:59], v[176:179], v[202:205], v[56:59]
	v_mfma_f32_16x16x32_bf16 v[52:55], v[186:189], v[202:205], v[52:55]
	v_mfma_f32_16x16x32_bf16 v[24:27], v[176:179], v[210:213], v[24:27]
	v_mfma_f32_16x16x32_bf16 v[20:23], v[186:189], v[210:213], v[20:23]
	v_mfma_f32_16x16x32_bf16 v[8:11], v[176:179], v[218:221], v[8:11]
	v_mfma_f32_16x16x32_bf16 v[4:7], v[186:189], v[218:221], v[4:7]
	v_mfma_f32_16x16x32_bf16 v[44:47], v[176:179], v[194:197], v[72:75]
	v_mfma_f32_16x16x32_bf16 v[48:51], v[186:189], v[194:197], v[68:71]
	v_mfma_f32_16x16x32_bf16 v[56:59], v[180:183], v[206:209], v[56:59]
	v_mfma_f32_16x16x32_bf16 v[52:55], v[190:193], v[206:209], v[52:55]
	v_mfma_f32_16x16x32_bf16 v[24:27], v[180:183], v[214:217], v[24:27]
	v_mfma_f32_16x16x32_bf16 v[20:23], v[190:193], v[214:217], v[20:23]
	v_mfma_f32_16x16x32_bf16 v[8:11], v[180:183], v[222:225], v[8:11]
	v_mfma_f32_16x16x32_bf16 v[4:7], v[190:193], v[222:225], v[4:7]
	v_mfma_f32_16x16x32_bf16 v[44:47], v[180:183], v[198:201], v[44:47]
	v_mfma_f32_16x16x32_bf16 v[48:51], v[190:193], v[198:201], v[48:51]
	s_setprio 0
	s_barrier
	s_add_i32 s3, 0, 0x18000
	v_add_u32_e32 v38, s3, v167
	s_add_i32 s42, 0, 0x1c000
	ds_read_b128 v[68:71], v38
	ds_read_b128 v[72:75], v38 offset:1024
	ds_read_b128 v[160:163], v38 offset:2048
	ds_read_b128 v[172:175], v38 offset:3072
	v_add_u32_e32 v38, s42, v167
	ds_read_b128 v[176:179], v38
	ds_read_b128 v[180:183], v38 offset:1024
	ds_read_b128 v[186:189], v38 offset:2048
	ds_read_b128 v[190:193], v38 offset:3072
	s_add_u32 s30, s30, 0x80000
	s_addc_u32 s31, s31, 0
	s_mov_b32 m0, s52
	v_lshl_add_u64 v[38:39], s[30:31], 0, v[0:1]
	ds_read_b128 v[194:197], v171 offset:32768
	ds_read_b128 v[198:201], v171 offset:33792
	ds_read_b128 v[202:205], v171 offset:34816
	ds_read_b128 v[206:209], v171 offset:35840
	ds_read_b128 v[210:213], v171 offset:36864
	ds_read_b128 v[214:217], v171 offset:37888
	ds_read_b128 v[218:221], v171 offset:38912
	ds_read_b128 v[222:225], v171 offset:39936
	global_load_lds_dwordx4 v[38:39], off
	v_lshl_add_u64 v[38:39], s[30:31], 0, v[148:149]
	s_mov_b32 m0, s53
	s_nop 0
	global_load_lds_dwordx4 v[38:39], off
	s_waitcnt vmcnt(8)
	s_waitcnt lgkmcnt(0)
	s_setprio 1
	s_barrier
	v_mfma_f32_16x16x32_bf16 v[144:147], v[68:71], v[194:197], v[144:147]
	v_mfma_f32_16x16x32_bf16 v[140:143], v[160:163], v[194:197], v[140:143]
	v_mfma_f32_16x16x32_bf16 v[136:139], v[176:179], v[194:197], v[136:139]
	v_mfma_f32_16x16x32_bf16 v[132:135], v[186:189], v[194:197], v[132:135]
	v_mfma_f32_16x16x32_bf16 v[128:131], v[68:71], v[202:205], v[128:131]
	v_mfma_f32_16x16x32_bf16 v[124:127], v[160:163], v[202:205], v[124:127]
	v_mfma_f32_16x16x32_bf16 v[120:123], v[176:179], v[202:205], v[120:123]
	v_mfma_f32_16x16x32_bf16 v[116:119], v[186:189], v[202:205], v[116:119]
	v_mfma_f32_16x16x32_bf16 v[112:115], v[68:71], v[210:213], v[112:115]
	v_mfma_f32_16x16x32_bf16 v[108:111], v[160:163], v[210:213], v[108:111]
	v_mfma_f32_16x16x32_bf16 v[104:107], v[176:179], v[210:213], v[104:107]
	v_mfma_f32_16x16x32_bf16 v[100:103], v[186:189], v[210:213], v[100:103]
	v_mfma_f32_16x16x32_bf16 v[96:99], v[68:71], v[218:221], v[96:99]
	v_mfma_f32_16x16x32_bf16 v[92:95], v[160:163], v[218:221], v[92:95]
	v_mfma_f32_16x16x32_bf16 v[88:91], v[176:179], v[218:221], v[88:91]
	v_mfma_f32_16x16x32_bf16 v[84:87], v[186:189], v[218:221], v[84:87]
	s_setprio 0
	s_setprio 1
	v_mfma_f32_16x16x32_bf16 v[144:147], v[72:75], v[198:201], v[144:147]
	v_mfma_f32_16x16x32_bf16 v[140:143], v[172:175], v[198:201], v[140:143]
	v_mfma_f32_16x16x32_bf16 v[136:139], v[180:183], v[198:201], v[136:139]
	v_mfma_f32_16x16x32_bf16 v[132:135], v[190:193], v[198:201], v[132:135]
	v_mfma_f32_16x16x32_bf16 v[128:131], v[72:75], v[206:209], v[128:131]
	v_mfma_f32_16x16x32_bf16 v[124:127], v[172:175], v[206:209], v[124:127]
	v_mfma_f32_16x16x32_bf16 v[120:123], v[180:183], v[206:209], v[120:123]
	v_mfma_f32_16x16x32_bf16 v[116:119], v[190:193], v[206:209], v[116:119]
	v_mfma_f32_16x16x32_bf16 v[112:115], v[72:75], v[214:217], v[112:115]
	v_mfma_f32_16x16x32_bf16 v[108:111], v[172:175], v[214:217], v[108:111]
	v_mfma_f32_16x16x32_bf16 v[104:107], v[180:183], v[214:217], v[104:107]
	v_mfma_f32_16x16x32_bf16 v[100:103], v[190:193], v[214:217], v[100:103]
	v_mfma_f32_16x16x32_bf16 v[96:99], v[72:75], v[222:225], v[96:99]
	v_mfma_f32_16x16x32_bf16 v[92:95], v[172:175], v[222:225], v[92:95]
	v_mfma_f32_16x16x32_bf16 v[88:91], v[180:183], v[222:225], v[88:91]
	v_mfma_f32_16x16x32_bf16 v[84:87], v[190:193], v[222:225], v[84:87]
	s_setprio 0
	s_barrier
; #define PG8_STAGE(bufoff, gbase, voff) do { _Pragma("unroll") for (int _i = 0; _i < 2; ++_i) \
;         __builtin_amdgcn_global_load_lds((const unsigned*)((const char*)(gbase) + (voff)[_i]), (PG8_LAS unsigned*)(lds + (bufoff) + ldsw + _i * 8192), 16, 0, 0); } while (0)
; #define PG8_LDA(dst, b, h) do { _Pragma("unroll") for (int m = 0; m < 4; ++m) _Pragma("unroll") for (int k = 0; k < 2; ++k) dst[m][k] = *(const PG8_LAS bf16x8*)(lds + PG8_SA(b, h) + aoff + m * 2048 + k * 1024); } while (0)
; #define PG8_MMA(ai, bj, At, Bt) do { __builtin_amdgcn_s_setprio(1); _Pragma("unroll") for (int m = 0; m < 4; ++m) _Pragma("unroll") for (int n = 0; n < 2; ++n) _Pragma("unroll") for (int k = 0; k < 2; ++k) \
;         acc[ai][bj][m][n] = __builtin_amdgcn_mfma_f32_16x16x32_bf16(Bt[n][k], At[m][k], acc[ai][bj][m][n], 0, 0, 0); __builtin_amdgcn_s_setprio(0); } while (0)
; #define PG8_WAIT_V(n) asm volatile("s_waitcnt vmcnt(" #n ")" ::: "memory")
; #define PG8_WAIT_L(n) asm volatile("s_waitcnt lgkmcnt(" #n ")" ::: "memory")
; #define PG8_BAR __builtin_amdgcn_s_barrier()
; #define PG8_SCHED __builtin_amdgcn_sched_barrier(0)
; template <class Epi, class Sched, bool ALIGN_EPI = false, bool SP2 = false>
; __device__ __forceinline__ void gemm_phase(PG8_LAS unsigned char* lds, const Gemm g, const Sched& S, const Epi& E, const int tid) {
;     ...
;             PG8_LDA(At, 1, 1); PG8_STAGE(PG8_SB(1, 0), b3, voffB); PG8_STAGE(PG8_SB(1, 1), b3 + hstep, voffB); PG8_STAGE(PG8_SA(1, 0), a3, voffA);
;             PG8_WAIT_V(8); PG8_WAIT_L(0); PG8_BAR; PG8_MMA(1, 0, At, B0); PG8_MMA(1, 1, At, B1); PG8_BAR; PG8_SCHED;
	s_add_i32 s3, s3, s44
	v_lshl_add_u64 v[38:39], v[164:165], 0, s[46:47]
	s_mov_b32 m0, s3
	ds_read_b128 v[194:197], v171 offset:49152
	ds_read_b128 v[198:201], v171 offset:50176
	ds_read_b128 v[202:205], v171 offset:51200
	ds_read_b128 v[206:209], v171 offset:52224
	ds_read_b128 v[210:213], v171 offset:53248
	ds_read_b128 v[214:217], v171 offset:54272
	ds_read_b128 v[218:221], v171 offset:55296
	ds_read_b128 v[222:225], v171 offset:56320
	global_load_lds_dwordx4 v[38:39], off
	s_add_i32 m0, s3, 0x2000
	s_add_u32 s28, s28, 0x80080
	v_lshl_add_u64 v[38:39], v[226:227], 0, s[46:47]
	s_addc_u32 s29, s29, 0
	s_add_i32 s3, s42, s44
	global_load_lds_dwordx4 v[38:39], off
	v_lshl_add_u64 v[38:39], s[28:29], 0, v[2:3]
	s_mov_b32 m0, s3
	s_nop 0
	global_load_lds_dwordx4 v[38:39], off
	v_lshl_add_u64 v[38:39], s[28:29], 0, v[150:151]
	s_add_i32 m0, s3, 0x2000
	s_nop 0
	global_load_lds_dwordx4 v[38:39], off
	v_lshl_add_u64 v[38:39], v[228:229], 0, s[46:47]
	s_mov_b32 m0, s5
	s_nop 0
	global_load_lds_dwordx4 v[38:39], off
	v_lshl_add_u64 v[38:39], v[230:231], 0, s[46:47]
	s_mov_b32 m0, s54
	s_nop 0
	global_load_lds_dwordx4 v[38:39], off
	s_waitcnt vmcnt(8)
	s_waitcnt lgkmcnt(0)
	s_setprio 1
	s_barrier
	v_mfma_f32_16x16x32_bf16 v[80:83], v[68:71], v[194:197], v[80:83]
	v_mfma_f32_16x16x32_bf16 v[76:79], v[160:163], v[194:197], v[76:79]
	v_mfma_f32_16x16x32_bf16 v[64:67], v[68:71], v[202:205], v[64:67]
	v_mfma_f32_16x16x32_bf16 v[60:63], v[160:163], v[202:205], v[60:63]
	v_mfma_f32_16x16x32_bf16 v[38:41], v[68:71], v[210:213], v[40:43]
	v_mfma_f32_16x16x32_bf16 v[34:37], v[160:163], v[210:213], v[34:37]
	v_mfma_f32_16x16x32_bf16 v[16:19], v[68:71], v[218:221], v[16:19]
	v_mfma_f32_16x16x32_bf16 v[12:15], v[160:163], v[218:221], v[12:15]
	v_mfma_f32_16x16x32_bf16 v[80:83], v[72:75], v[198:201], v[80:83]
	v_mfma_f32_16x16x32_bf16 v[76:79], v[172:175], v[198:201], v[76:79]
	v_mfma_f32_16x16x32_bf16 v[64:67], v[72:75], v[206:209], v[64:67]
	v_mfma_f32_16x16x32_bf16 v[60:63], v[172:175], v[206:209], v[60:63]
	v_mfma_f32_16x16x32_bf16 v[40:43], v[72:75], v[214:217], v[38:41]
	v_mfma_f32_16x16x32_bf16 v[36:39], v[172:175], v[214:217], v[34:37]
	v_mfma_f32_16x16x32_bf16 v[16:19], v[72:75], v[222:225], v[16:19]
	v_mfma_f32_16x16x32_bf16 v[12:15], v[172:175], v[222:225], v[12:15]
	s_setprio 0
	s_setprio 1
	v_mfma_f32_16x16x32_bf16 v[44:47], v[176:179], v[194:197], v[44:47]
	v_mfma_f32_16x16x32_bf16 v[72:75], v[180:183], v[198:201], v[44:47]
	v_mfma_f32_16x16x32_bf16 v[44:47], v[186:189], v[194:197], v[48:51]
	v_mfma_f32_16x16x32_bf16 v[68:71], v[190:193], v[198:201], v[44:47]
	v_mfma_f32_16x16x32_bf16 v[44:47], v[176:179], v[202:205], v[56:59]
	v_mfma_f32_16x16x32_bf16 v[56:59], v[180:183], v[206:209], v[44:47]
	v_mfma_f32_16x16x32_bf16 v[44:47], v[186:189], v[202:205], v[52:55]
	v_mfma_f32_16x16x32_bf16 v[24:27], v[176:179], v[210:213], v[24:27]
	v_mfma_f32_16x16x32_bf16 v[20:23], v[186:189], v[210:213], v[20:23]
	v_mfma_f32_16x16x32_bf16 v[8:11], v[176:179], v[218:221], v[8:11]
	v_mfma_f32_16x16x32_bf16 v[4:7], v[186:189], v[218:221], v[4:7]
	v_mfma_f32_16x16x32_bf16 v[52:55], v[190:193], v[206:209], v[44:47]
	v_mfma_f32_16x16x32_bf16 v[24:27], v[180:183], v[214:217], v[24:27]
	v_mfma_f32_16x16x32_bf16 v[20:23], v[190:193], v[214:217], v[20:23]
	v_mfma_f32_16x16x32_bf16 v[8:11], v[180:183], v[222:225], v[8:11]
	v_mfma_f32_16x16x32_bf16 v[4:7], v[190:193], v[222:225], v[4:7]
	s_setprio 0
	s_barrier
	s_add_i32 s50, s50, 2
	s_add_u32 s26, s26, 0x100
	s_addc_u32 s27, s27, 0
	s_add_u32 s23, s23, 0x100
	s_addc_u32 s25, s25, 0
	s_cmp_gt_u32 s50, 29
	s_cbranch_scc1 .LBB0_159

; #define PG8_STAGE(bufoff, gbase, voff) do { _Pragma("unroll") for (int _i = 0; _i < 2; ++_i) \
;         __builtin_amdgcn_global_load_lds((const unsigned*)((const char*)(gbase) + (voff)[_i]), (PG8_LAS unsigned*)(lds + (bufoff) + ldsw + _i * 8192), 16, 0, 0); } while (0)
; #define PG8_LDA(dst, b, h) do { _Pragma("unroll") for (int m = 0; m < 4; ++m) _Pragma("unroll") for (int k = 0; k < 2; ++k) dst[m][k] = *(const PG8_LAS bf16x8*)(lds + PG8_SA(b, h) + aoff + m * 2048 + k * 1024); } while (0)
; #define PG8_LDB(dst, b, h) do { _Pragma("unroll") for (int n = 0; n < 2; ++n) _Pragma("unroll") for (int k = 0; k < 2; ++k) dst[n][k] = *(const PG8_LAS bf16x8*)(lds + PG8_SB(b, h) + boff + n * 2048 + k * 1024); } while (0)
; #define PG8_MMA(ai, bj, At, Bt) do { __builtin_amdgcn_s_setprio(1); _Pragma("unroll") for (int m = 0; m < 4; ++m) _Pragma("unroll") for (int n = 0; n < 2; ++n) _Pragma("unroll") for (int k = 0; k < 2; ++k) \
;         acc[ai][bj][m][n] = __builtin_amdgcn_mfma_f32_16x16x32_bf16(Bt[n][k], At[m][k], acc[ai][bj][m][n], 0, 0, 0); __builtin_amdgcn_s_setprio(0); } while (0)
; #define PG8_WAIT_V(n) asm volatile("s_waitcnt vmcnt(" #n ")" ::: "memory")
; #define PG8_BAR __builtin_amdgcn_s_barrier()
; template <class Epi, class Sched, bool ALIGN_EPI = false, bool SP2 = false>
; __device__ __forceinline__ void gemm_phase(PG8_LAS unsigned char* lds, const Gemm g, const Sched& S, const Epi& E, const int tid) {
;     ...
;             const char* a1 = cA + (size_t)(t + 1) * kstep;
;             const char* a2 = last ? nA : cA + (size_t)(t + 2) * kstep; const char* b2 = last ? nB : cB + (size_t)(t + 2) * kstep;
;             const char* a3 = a2 + kstep; const char* b3 = b2 + kstep;
;             if (last && has_next) S.a_ready(nxt);
;             if (last) E.prefetch(lds + EPI_LDS_OFF + wid * 1024, cur, wr, wc, lane);
;             if constexpr (SP2) {
;             PG8_LDB(B0, 0, 0); PG8_LDB(B1, 0, 1); PG8_SCHED; PG8_LDA(At, 0, 0); PG8_STAGE(PG8_SA(1, 1), a1 + hstep, voffA);
;             PG8_WAIT_V(8); PG8_WAIT_L(0); PG8_BAR; PG8_MMA(0, 0, At, B0); PG8_MMA(0, 1, At, B1); PG8_BAR; PG8_SCHED;
;             PG8_LDA(At, 0, 1); PG8_STAGE(PG8_SB(0, 0), b2, voffB); PG8_STAGE(PG8_SB(0, 1), b2 + hstep, voffB); PG8_STAGE(PG8_SA(0, 0), a2, voffA);
;             PG8_WAIT_V(8); PG8_WAIT_L(0); PG8_BAR; PG8_MMA(1, 0, At, B0); PG8_MMA(1, 1, At, B1); PG8_BAR; PG8_SCHED;
.LBB0_228:
	s_add_u32 s22, s20, 0x100
	s_addc_u32 s23, s21, 0
	s_and_b64 s[24:25], s[24:25], exec
	s_cselect_b32 s27, s11, s23
	s_cselect_b32 s26, s10, s22
	s_cselect_b32 s25, s17, s75
	s_cselect_b32 s24, s16, s74
	s_add_i32 s42, 0, 0x10000
	s_add_i32 s43, 0, 0x14000
	v_add_u32_e32 v146, s42, v220
	v_add_u32_e32 v162, s43, v220
	ds_read_b128 v[134:137], v146
	ds_read_b128 v[138:141], v146 offset:1024
	ds_read_b128 v[142:145], v146 offset:2048
	ds_read_b128 v[146:149], v146 offset:3072
	ds_read_b128 v[150:153], v162
	ds_read_b128 v[154:157], v162 offset:1024
	ds_read_b128 v[158:161], v162 offset:2048
	ds_read_b128 v[172:175], v162 offset:3072
	v_lshl_add_u64 v[162:163], s[20:21], 0, v[168:169]
	s_add_i32 m0, s30, 0xc000
	ds_read_b128 v[176:179], v226
	ds_read_b128 v[186:189], v226 offset:1024
	ds_read_b128 v[190:193], v226 offset:2048
	ds_read_b128 v[194:197], v226 offset:3072
	ds_read_b128 v[198:201], v226 offset:4096
	ds_read_b128 v[202:205], v226 offset:5120
	ds_read_b128 v[206:209], v226 offset:6144
	ds_read_b128 v[210:213], v226 offset:7168
	global_load_lds_dwordx4 v[162:163], off
	v_lshl_add_u64 v[162:163], s[20:21], 0, v[170:171]
	s_add_i32 m0, s30, 0xe000
	s_nop 0
	global_load_lds_dwordx4 v[162:163], off
	s_waitcnt vmcnt(8)
	s_waitcnt lgkmcnt(0)
	s_setprio 1
	s_barrier
	v_mfma_f32_16x16x32_bf16 v[128:131], v[134:137], v[176:179], v[128:131]
	v_mfma_f32_16x16x32_bf16 v[124:127], v[142:145], v[176:179], v[124:127]
	v_mfma_f32_16x16x32_bf16 v[120:123], v[150:153], v[176:179], v[120:123]
	v_mfma_f32_16x16x32_bf16 v[116:119], v[158:161], v[176:179], v[116:119]
	v_mfma_f32_16x16x32_bf16 v[112:115], v[134:137], v[190:193], v[112:115]
	v_mfma_f32_16x16x32_bf16 v[108:111], v[142:145], v[190:193], v[108:111]
	v_mfma_f32_16x16x32_bf16 v[104:107], v[150:153], v[190:193], v[104:107]
	v_mfma_f32_16x16x32_bf16 v[100:103], v[158:161], v[190:193], v[100:103]
	v_mfma_f32_16x16x32_bf16 v[96:99], v[134:137], v[198:201], v[96:99]
	v_mfma_f32_16x16x32_bf16 v[92:95], v[142:145], v[198:201], v[92:95]
	v_mfma_f32_16x16x32_bf16 v[88:91], v[150:153], v[198:201], v[88:91]
	v_mfma_f32_16x16x32_bf16 v[84:87], v[158:161], v[198:201], v[84:87]
	v_mfma_f32_16x16x32_bf16 v[80:83], v[134:137], v[206:209], v[80:83]
	v_mfma_f32_16x16x32_bf16 v[76:79], v[142:145], v[206:209], v[76:79]
	v_mfma_f32_16x16x32_bf16 v[72:75], v[150:153], v[206:209], v[72:75]
	v_mfma_f32_16x16x32_bf16 v[68:71], v[158:161], v[206:209], v[68:71]
	s_setprio 0
	s_setprio 1
	v_mfma_f32_16x16x32_bf16 v[128:131], v[138:141], v[186:189], v[128:131]
	v_mfma_f32_16x16x32_bf16 v[124:127], v[146:149], v[186:189], v[124:127]
	v_mfma_f32_16x16x32_bf16 v[120:123], v[154:157], v[186:189], v[120:123]
	v_mfma_f32_16x16x32_bf16 v[116:119], v[172:175], v[186:189], v[116:119]
	v_mfma_f32_16x16x32_bf16 v[112:115], v[138:141], v[194:197], v[112:115]
	v_mfma_f32_16x16x32_bf16 v[108:111], v[146:149], v[194:197], v[108:111]
	v_mfma_f32_16x16x32_bf16 v[104:107], v[154:157], v[194:197], v[104:107]
	v_mfma_f32_16x16x32_bf16 v[100:103], v[172:175], v[194:197], v[100:103]
	v_mfma_f32_16x16x32_bf16 v[96:99], v[138:141], v[202:205], v[96:99]
	v_mfma_f32_16x16x32_bf16 v[92:95], v[146:149], v[202:205], v[92:95]
	v_mfma_f32_16x16x32_bf16 v[88:91], v[154:157], v[202:205], v[88:91]
	v_mfma_f32_16x16x32_bf16 v[84:87], v[172:175], v[202:205], v[84:87]
	v_mfma_f32_16x16x32_bf16 v[80:83], v[138:141], v[210:213], v[80:83]
	v_mfma_f32_16x16x32_bf16 v[76:79], v[146:149], v[210:213], v[76:79]
	v_mfma_f32_16x16x32_bf16 v[72:75], v[154:157], v[210:213], v[72:75]
	v_mfma_f32_16x16x32_bf16 v[68:71], v[172:175], v[210:213], v[68:71]
	s_setprio 0
	s_barrier
	s_add_i32 s20, s42, s29
	v_lshl_add_u64 v[162:163], s[24:25], 0, v[2:3]
	s_mov_b32 m0, s20
	ds_read_b128 v[176:179], v226 offset:16384
	ds_read_b128 v[186:189], v226 offset:17408
	ds_read_b128 v[190:193], v226 offset:18432
	ds_read_b128 v[194:197], v226 offset:19456
	ds_read_b128 v[198:201], v226 offset:20480
	ds_read_b128 v[202:205], v226 offset:21504
	ds_read_b128 v[206:209], v226 offset:22528
	ds_read_b128 v[210:213], v226 offset:23552
	global_load_lds_dwordx4 v[162:163], off
	s_add_i32 m0, s20, 0x2000
	s_add_u32 s20, s24, 0x160000
	v_lshl_add_u64 v[180:181], s[24:25], 0, v[166:167]
	s_addc_u32 s21, s25, 0
	s_add_i32 s42, s43, s29
	global_load_lds_dwordx4 v[180:181], off
	v_lshl_add_u64 v[182:183], s[20:21], 0, v[2:3]
	s_mov_b32 m0, s42
	v_lshl_add_u64 v[214:215], s[26:27], 0, v[164:165]
	global_load_lds_dwordx4 v[182:183], off
	v_lshl_add_u64 v[182:183], s[20:21], 0, v[166:167]
	s_add_i32 m0, s42, 0x2000
	s_nop 0
	global_load_lds_dwordx4 v[182:183], off
	v_lshl_add_u64 v[182:183], s[26:27], 0, v[0:1]
	s_mov_b32 m0, s30
	s_nop 0
	global_load_lds_dwordx4 v[182:183], off
	s_mov_b32 m0, s31
	s_nop 0
	global_load_lds_dwordx4 v[214:215], off
	s_waitcnt vmcnt(8)
	s_waitcnt lgkmcnt(0)
	s_setprio 1
	s_barrier
; #define PG8_STAGE(bufoff, gbase, voff) do { _Pragma("unroll") for (int _i = 0; _i < 2; ++_i) \
;         __builtin_amdgcn_global_load_lds((const unsigned*)((const char*)(gbase) + (voff)[_i]), (PG8_LAS unsigned*)(lds + (bufoff) + ldsw + _i * 8192), 16, 0, 0); } while (0)
; #define PG8_LDA(dst, b, h) do { _Pragma("unroll") for (int m = 0; m < 4; ++m) _Pragma("unroll") for (int k = 0; k < 2; ++k) dst[m][k] = *(const PG8_LAS bf16x8*)(lds + PG8_SA(b, h) + aoff + m * 2048 + k * 1024); } while (0)
; #define PG8_LDB(dst, b, h) do { _Pragma("unroll") for (int n = 0; n < 2; ++n) _Pragma("unroll") for (int k = 0; k < 2; ++k) dst[n][k] = *(const PG8_LAS bf16x8*)(lds + PG8_SB(b, h) + boff + n * 2048 + k * 1024); } while (0)
; #define PG8_MMA(ai, bj, At, Bt) do { __builtin_amdgcn_s_setprio(1); _Pragma("unroll") for (int m = 0; m < 4; ++m) _Pragma("unroll") for (int n = 0; n < 2; ++n) _Pragma("unroll") for (int k = 0; k < 2; ++k) \
;         acc[ai][bj][m][n] = __builtin_amdgcn_mfma_f32_16x16x32_bf16(Bt[n][k], At[m][k], acc[ai][bj][m][n], 0, 0, 0); __builtin_amdgcn_s_setprio(0); } while (0)
; #define PG8_WAIT_V(n) asm volatile("s_waitcnt vmcnt(" #n ")" ::: "memory")
; #define PG8_WAIT_L(n) asm volatile("s_waitcnt lgkmcnt(" #n ")" ::: "memory")
; #define PG8_BAR __builtin_amdgcn_s_barrier()
; #define PG8_SCHED __builtin_amdgcn_sched_barrier(0)
; template <class Epi, class Sched, bool ALIGN_EPI = false, bool SP2 = false>
; __device__ __forceinline__ void gemm_phase(PG8_LAS unsigned char* lds, const Gemm g, const Sched& S, const Epi& E, const int tid) {
;     ...
;             PG8_WAIT_V(8); PG8_WAIT_L(0); PG8_BAR; PG8_MMA(1, 0, At, B0); PG8_MMA(1, 1, At, B1); PG8_BAR; PG8_SCHED;
;             PG8_LDB(B0, 1, 0); PG8_LDB(B1, 1, 1); PG8_SCHED; PG8_LDA(At, 1, 0); PG8_STAGE(PG8_SA(0, 1), a2 + hstep, voffA);
;             PG8_WAIT_V(8); PG8_WAIT_L(0); PG8_BAR; PG8_MMA(0, 0, At, B0); PG8_MMA(0, 1, At, B1); PG8_BAR; PG8_SCHED;
	v_mfma_f32_16x16x32_bf16 v[64:67], v[134:137], v[176:179], v[64:67]
	v_mfma_f32_16x16x32_bf16 v[60:63], v[142:145], v[176:179], v[60:63]
	v_mfma_f32_16x16x32_bf16 v[56:59], v[150:153], v[176:179], v[56:59]
	v_mfma_f32_16x16x32_bf16 v[52:55], v[158:161], v[176:179], v[52:55]
	v_mfma_f32_16x16x32_bf16 v[48:51], v[134:137], v[190:193], v[48:51]
	v_mfma_f32_16x16x32_bf16 v[44:47], v[142:145], v[190:193], v[44:47]
	v_mfma_f32_16x16x32_bf16 v[40:43], v[150:153], v[190:193], v[40:43]
	v_mfma_f32_16x16x32_bf16 v[36:39], v[158:161], v[190:193], v[36:39]
	v_mfma_f32_16x16x32_bf16 v[32:35], v[134:137], v[198:201], v[32:35]
	v_mfma_f32_16x16x32_bf16 v[28:31], v[142:145], v[198:201], v[28:31]
	v_mfma_f32_16x16x32_bf16 v[24:27], v[150:153], v[198:201], v[24:27]
	v_mfma_f32_16x16x32_bf16 v[20:23], v[158:161], v[198:201], v[20:23]
	v_mfma_f32_16x16x32_bf16 v[16:19], v[134:137], v[206:209], v[16:19]
	v_mfma_f32_16x16x32_bf16 v[12:15], v[142:145], v[206:209], v[12:15]
	v_mfma_f32_16x16x32_bf16 v[8:11], v[150:153], v[206:209], v[8:11]
	v_mfma_f32_16x16x32_bf16 v[4:7], v[158:161], v[206:209], v[4:7]
	s_setprio 0
	s_setprio 1
	v_mfma_f32_16x16x32_bf16 v[64:67], v[138:141], v[186:189], v[64:67]
	v_mfma_f32_16x16x32_bf16 v[60:63], v[146:149], v[186:189], v[60:63]
	v_mfma_f32_16x16x32_bf16 v[56:59], v[154:157], v[186:189], v[56:59]
	v_mfma_f32_16x16x32_bf16 v[52:55], v[172:175], v[186:189], v[52:55]
	v_mfma_f32_16x16x32_bf16 v[48:51], v[138:141], v[194:197], v[48:51]
	v_mfma_f32_16x16x32_bf16 v[44:47], v[146:149], v[194:197], v[44:47]
	v_mfma_f32_16x16x32_bf16 v[40:43], v[154:157], v[194:197], v[40:43]
	v_mfma_f32_16x16x32_bf16 v[36:39], v[172:175], v[194:197], v[36:39]
	v_mfma_f32_16x16x32_bf16 v[32:35], v[138:141], v[202:205], v[32:35]
	v_mfma_f32_16x16x32_bf16 v[28:31], v[146:149], v[202:205], v[28:31]
	v_mfma_f32_16x16x32_bf16 v[24:27], v[154:157], v[202:205], v[24:27]
	v_mfma_f32_16x16x32_bf16 v[20:23], v[172:175], v[202:205], v[20:23]
	v_mfma_f32_16x16x32_bf16 v[16:19], v[138:141], v[210:213], v[16:19]
	v_mfma_f32_16x16x32_bf16 v[12:15], v[146:149], v[210:213], v[12:15]
	v_mfma_f32_16x16x32_bf16 v[8:11], v[154:157], v[210:213], v[8:11]
	v_mfma_f32_16x16x32_bf16 v[4:7], v[172:175], v[210:213], v[4:7]
	s_setprio 0
	s_barrier
	s_add_i32 s42, 0, 0x18000
	s_add_i32 s43, 0, 0x1c000
	v_add_u32_e32 v146, s42, v220
	v_add_u32_e32 v172, s43, v220
	ds_read_b128 v[134:137], v146
	ds_read_b128 v[138:141], v146 offset:1024
	ds_read_b128 v[142:145], v146 offset:2048
	ds_read_b128 v[146:149], v146 offset:3072
	ds_read_b128 v[150:153], v172
	ds_read_b128 v[154:157], v172 offset:1024
	ds_read_b128 v[158:161], v172 offset:2048
	ds_read_b128 v[172:175], v172 offset:3072
	s_add_u32 s20, s26, 0x160000
	s_addc_u32 s21, s27, 0
	s_mov_b32 m0, s36
	v_lshl_add_u64 v[216:217], s[20:21], 0, v[0:1]
	ds_read_b128 v[176:179], v226 offset:32768
	ds_read_b128 v[186:189], v226 offset:33792
	ds_read_b128 v[190:193], v226 offset:34816
	ds_read_b128 v[194:197], v226 offset:35840
	ds_read_b128 v[198:201], v226 offset:36864
	ds_read_b128 v[202:205], v226 offset:37888
	ds_read_b128 v[206:209], v226 offset:38912
	ds_read_b128 v[210:213], v226 offset:39936
	global_load_lds_dwordx4 v[216:217], off
	v_lshl_add_u64 v[216:217], s[20:21], 0, v[164:165]
	s_mov_b32 m0, s37
	s_nop 0
	global_load_lds_dwordx4 v[216:217], off
	s_waitcnt vmcnt(8)
	s_waitcnt lgkmcnt(0)
	s_setprio 1
	s_barrier
	v_mfma_f32_16x16x32_bf16 v[128:131], v[134:137], v[176:179], v[128:131]
	v_mfma_f32_16x16x32_bf16 v[124:127], v[142:145], v[176:179], v[124:127]
	v_mfma_f32_16x16x32_bf16 v[120:123], v[150:153], v[176:179], v[120:123]
	v_mfma_f32_16x16x32_bf16 v[116:119], v[158:161], v[176:179], v[116:119]
	v_mfma_f32_16x16x32_bf16 v[112:115], v[134:137], v[190:193], v[112:115]
	v_mfma_f32_16x16x32_bf16 v[108:111], v[142:145], v[190:193], v[108:111]
	v_mfma_f32_16x16x32_bf16 v[104:107], v[150:153], v[190:193], v[104:107]
	v_mfma_f32_16x16x32_bf16 v[100:103], v[158:161], v[190:193], v[100:103]
	v_mfma_f32_16x16x32_bf16 v[96:99], v[134:137], v[198:201], v[96:99]
	v_mfma_f32_16x16x32_bf16 v[92:95], v[142:145], v[198:201], v[92:95]
	v_mfma_f32_16x16x32_bf16 v[88:91], v[150:153], v[198:201], v[88:91]
	v_mfma_f32_16x16x32_bf16 v[84:87], v[158:161], v[198:201], v[84:87]
	v_mfma_f32_16x16x32_bf16 v[80:83], v[134:137], v[206:209], v[80:83]
	v_mfma_f32_16x16x32_bf16 v[76:79], v[142:145], v[206:209], v[76:79]
	v_mfma_f32_16x16x32_bf16 v[72:75], v[150:153], v[206:209], v[72:75]
	v_mfma_f32_16x16x32_bf16 v[68:71], v[158:161], v[206:209], v[68:71]
	s_setprio 0
	s_setprio 1
	v_mfma_f32_16x16x32_bf16 v[128:131], v[138:141], v[186:189], v[128:131]
	v_mfma_f32_16x16x32_bf16 v[124:127], v[146:149], v[186:189], v[124:127]
	v_mfma_f32_16x16x32_bf16 v[120:123], v[154:157], v[186:189], v[120:123]
	v_mfma_f32_16x16x32_bf16 v[116:119], v[172:175], v[186:189], v[116:119]
	v_mfma_f32_16x16x32_bf16 v[112:115], v[138:141], v[194:197], v[112:115]
	v_mfma_f32_16x16x32_bf16 v[108:111], v[146:149], v[194:197], v[108:111]
	v_mfma_f32_16x16x32_bf16 v[104:107], v[154:157], v[194:197], v[104:107]
	v_mfma_f32_16x16x32_bf16 v[100:103], v[172:175], v[194:197], v[100:103]
	v_mfma_f32_16x16x32_bf16 v[96:99], v[138:141], v[202:205], v[96:99]
	v_mfma_f32_16x16x32_bf16 v[92:95], v[146:149], v[202:205], v[92:95]
	v_mfma_f32_16x16x32_bf16 v[88:91], v[154:157], v[202:205], v[88:91]
	v_mfma_f32_16x16x32_bf16 v[84:87], v[172:175], v[202:205], v[84:87]
	v_mfma_f32_16x16x32_bf16 v[80:83], v[138:141], v[210:213], v[80:83]
	v_mfma_f32_16x16x32_bf16 v[76:79], v[146:149], v[210:213], v[76:79]
	v_mfma_f32_16x16x32_bf16 v[72:75], v[154:157], v[210:213], v[72:75]
	v_mfma_f32_16x16x32_bf16 v[68:71], v[172:175], v[210:213], v[68:71]
	s_setprio 0
	s_barrier
; #define PG8_STAGE(bufoff, gbase, voff) do { _Pragma("unroll") for (int _i = 0; _i < 2; ++_i) \
;         __builtin_amdgcn_global_load_lds((const unsigned*)((const char*)(gbase) + (voff)[_i]), (PG8_LAS unsigned*)(lds + (bufoff) + ldsw + _i * 8192), 16, 0, 0); } while (0)
; #define PG8_LDA(dst, b, h) do { _Pragma("unroll") for (int m = 0; m < 4; ++m) _Pragma("unroll") for (int k = 0; k < 2; ++k) dst[m][k] = *(const PG8_LAS bf16x8*)(lds + PG8_SA(b, h) + aoff + m * 2048 + k * 1024); } while (0)
; #define PG8_MMA(ai, bj, At, Bt) do { __builtin_amdgcn_s_setprio(1); _Pragma("unroll") for (int m = 0; m < 4; ++m) _Pragma("unroll") for (int n = 0; n < 2; ++n) _Pragma("unroll") for (int k = 0; k < 2; ++k) \
;         acc[ai][bj][m][n] = __builtin_amdgcn_mfma_f32_16x16x32_bf16(Bt[n][k], At[m][k], acc[ai][bj][m][n], 0, 0, 0); __builtin_amdgcn_s_setprio(0); } while (0)
; #define PG8_WAIT_V(n) asm volatile("s_waitcnt vmcnt(" #n ")" ::: "memory")
; #define PG8_WAIT_L(n) asm volatile("s_waitcnt lgkmcnt(" #n ")" ::: "memory")
; #define PG8_BAR __builtin_amdgcn_s_barrier()
; #define PG8_SCHED __builtin_amdgcn_sched_barrier(0)
; template <class Epi, class Sched, bool ALIGN_EPI = false, bool SP2 = false>
; __device__ __forceinline__ void gemm_phase(PG8_LAS unsigned char* lds, const Gemm g, const Sched& S, const Epi& E, const int tid) {
;     ...
;             PG8_LDA(At, 1, 1); PG8_STAGE(PG8_SB(1, 0), b3, voffB); PG8_STAGE(PG8_SB(1, 1), b3 + hstep, voffB); PG8_STAGE(PG8_SA(1, 0), a3, voffA);
;             PG8_WAIT_V(8); PG8_WAIT_L(0); PG8_BAR; PG8_MMA(1, 0, At, B0); PG8_MMA(1, 1, At, B1); PG8_BAR; PG8_SCHED;
	s_add_i32 s20, s42, s29
	v_lshl_add_u64 v[162:163], v[162:163], 0, s[46:47]
	s_mov_b32 m0, s20
	ds_read_b128 v[176:179], v226 offset:49152
	ds_read_b128 v[186:189], v226 offset:50176
	ds_read_b128 v[190:193], v226 offset:51200
	ds_read_b128 v[194:197], v226 offset:52224
	ds_read_b128 v[198:201], v226 offset:53248
	ds_read_b128 v[202:205], v226 offset:54272
	ds_read_b128 v[206:209], v226 offset:55296
	ds_read_b128 v[210:213], v226 offset:56320
	global_load_lds_dwordx4 v[162:163], off
	s_add_i32 m0, s20, 0x2000
	s_add_u32 s20, s24, 0x160080
	v_lshl_add_u64 v[162:163], v[180:181], 0, s[46:47]
	s_addc_u32 s21, s25, 0
	s_add_i32 s24, s43, s29
	global_load_lds_dwordx4 v[162:163], off
	v_lshl_add_u64 v[162:163], s[20:21], 0, v[2:3]
	s_mov_b32 m0, s24
	s_nop 0
	global_load_lds_dwordx4 v[162:163], off
	v_lshl_add_u64 v[162:163], s[20:21], 0, v[166:167]
	s_add_i32 m0, s24, 0x2000
	s_nop 0
	global_load_lds_dwordx4 v[162:163], off
	v_lshl_add_u64 v[162:163], v[182:183], 0, s[46:47]
	s_mov_b32 m0, s39
	s_nop 0
	global_load_lds_dwordx4 v[162:163], off
	v_lshl_add_u64 v[162:163], v[214:215], 0, s[46:47]
	s_mov_b32 m0, s44
	s_nop 0
	global_load_lds_dwordx4 v[162:163], off
	s_waitcnt vmcnt(8)
	s_waitcnt lgkmcnt(0)
	s_setprio 1
	s_barrier
	v_mfma_f32_16x16x32_bf16 v[64:67], v[134:137], v[176:179], v[64:67]
	v_mfma_f32_16x16x32_bf16 v[60:63], v[142:145], v[176:179], v[60:63]
	v_mfma_f32_16x16x32_bf16 v[56:59], v[150:153], v[176:179], v[56:59]
	v_mfma_f32_16x16x32_bf16 v[52:55], v[158:161], v[176:179], v[52:55]
	v_mfma_f32_16x16x32_bf16 v[48:51], v[134:137], v[190:193], v[48:51]
	v_mfma_f32_16x16x32_bf16 v[44:47], v[142:145], v[190:193], v[44:47]
	v_mfma_f32_16x16x32_bf16 v[40:43], v[150:153], v[190:193], v[40:43]
	v_mfma_f32_16x16x32_bf16 v[36:39], v[158:161], v[190:193], v[36:39]
	v_mfma_f32_16x16x32_bf16 v[32:35], v[134:137], v[198:201], v[32:35]
	v_mfma_f32_16x16x32_bf16 v[28:31], v[142:145], v[198:201], v[28:31]
	v_mfma_f32_16x16x32_bf16 v[24:27], v[150:153], v[198:201], v[24:27]
	v_mfma_f32_16x16x32_bf16 v[20:23], v[158:161], v[198:201], v[20:23]
	v_mfma_f32_16x16x32_bf16 v[16:19], v[134:137], v[206:209], v[16:19]
	v_mfma_f32_16x16x32_bf16 v[12:15], v[142:145], v[206:209], v[12:15]
	v_mfma_f32_16x16x32_bf16 v[8:11], v[150:153], v[206:209], v[8:11]
	v_mfma_f32_16x16x32_bf16 v[4:7], v[158:161], v[206:209], v[4:7]
	s_setprio 0
	s_setprio 1
	v_mfma_f32_16x16x32_bf16 v[64:67], v[138:141], v[186:189], v[64:67]
	v_mfma_f32_16x16x32_bf16 v[60:63], v[146:149], v[186:189], v[60:63]
	v_mfma_f32_16x16x32_bf16 v[56:59], v[154:157], v[186:189], v[56:59]
	v_mfma_f32_16x16x32_bf16 v[52:55], v[172:175], v[186:189], v[52:55]
	v_mfma_f32_16x16x32_bf16 v[48:51], v[138:141], v[194:197], v[48:51]
	v_mfma_f32_16x16x32_bf16 v[44:47], v[146:149], v[194:197], v[44:47]
	v_mfma_f32_16x16x32_bf16 v[40:43], v[154:157], v[194:197], v[40:43]
	v_mfma_f32_16x16x32_bf16 v[36:39], v[172:175], v[194:197], v[36:39]
	v_mfma_f32_16x16x32_bf16 v[32:35], v[138:141], v[202:205], v[32:35]
	v_mfma_f32_16x16x32_bf16 v[28:31], v[146:149], v[202:205], v[28:31]
	v_mfma_f32_16x16x32_bf16 v[24:27], v[154:157], v[202:205], v[24:27]
	v_mfma_f32_16x16x32_bf16 v[20:23], v[172:175], v[202:205], v[20:23]
	v_mfma_f32_16x16x32_bf16 v[16:19], v[138:141], v[210:213], v[16:19]
	v_mfma_f32_16x16x32_bf16 v[12:15], v[146:149], v[210:213], v[12:15]
	v_mfma_f32_16x16x32_bf16 v[8:11], v[154:157], v[210:213], v[8:11]
	v_mfma_f32_16x16x32_bf16 v[4:7], v[172:175], v[210:213], v[4:7]
	s_setprio 0
	s_barrier
	s_add_i32 s84, s84, 2
	s_add_u32 s74, s74, 0x100
	s_addc_u32 s75, s75, 0
	s_cmpk_gt_u32 s84, 0x55
	s_mov_b64 s[20:21], s[22:23]
	s_cbranch_scc1 .LBB0_231

; #define PG8_STAGE(bufoff, gbase, voff) do { _Pragma("unroll") for (int _i = 0; _i < 2; ++_i) \
;         __builtin_amdgcn_global_load_lds((const unsigned*)((const char*)(gbase) + (voff)[_i]), (PG8_LAS unsigned*)(lds + (bufoff) + ldsw + _i * 8192), 16, 0, 0); } while (0)
; #define PG8_LDA(dst, b, h) do { _Pragma("unroll") for (int m = 0; m < 4; ++m) _Pragma("unroll") for (int k = 0; k < 2; ++k) dst[m][k] = *(const PG8_LAS bf16x8*)(lds + PG8_SA(b, h) + aoff + m * 2048 + k * 1024); } while (0)
; #define PG8_LDB(dst, b, h) do { _Pragma("unroll") for (int n = 0; n < 2; ++n) _Pragma("unroll") for (int k = 0; k < 2; ++k) dst[n][k] = *(const PG8_LAS bf16x8*)(lds + PG8_SB(b, h) + boff + n * 2048 + k * 1024); } while (0)
; #define PG8_MMA(ai, bj, At, Bt) do { __builtin_amdgcn_s_setprio(1); _Pragma("unroll") for (int m = 0; m < 4; ++m) _Pragma("unroll") for (int n = 0; n < 2; ++n) _Pragma("unroll") for (int k = 0; k < 2; ++k) \
;         acc[ai][bj][m][n] = __builtin_amdgcn_mfma_f32_16x16x32_bf16(Bt[n][k], At[m][k], acc[ai][bj][m][n], 0, 0, 0); __builtin_amdgcn_s_setprio(0); } while (0)
; #define PG8_WAIT_V(n) asm volatile("s_waitcnt vmcnt(" #n ")" ::: "memory")
; #define PG8_BAR __builtin_amdgcn_s_barrier()
; template <class Epi, class Sched, bool ALIGN_EPI = false, bool SP2 = false>
; __device__ __forceinline__ void gemm_phase(PG8_LAS unsigned char* lds, const Gemm g, const Sched& S, const Epi& E, const int tid) {
;     ...
;             const char* a1 = cA + (size_t)(t + 1) * kstep;
;             const char* a2 = last ? nA : cA + (size_t)(t + 2) * kstep; const char* b2 = last ? nB : cB + (size_t)(t + 2) * kstep;
;             const char* a3 = a2 + kstep; const char* b3 = b2 + kstep;
;             if (last && has_next) S.a_ready(nxt);
;             if (last) E.prefetch(lds + EPI_LDS_OFF + wid * 1024, cur, wr, wc, lane);
;             if constexpr (SP2) {
;             PG8_LDB(B0, 0, 0); PG8_LDB(B1, 0, 1); PG8_SCHED; PG8_LDA(At, 0, 0); PG8_STAGE(PG8_SA(1, 1), a1 + hstep, voffA);
;             PG8_WAIT_V(8); PG8_WAIT_L(0); PG8_BAR; PG8_MMA(0, 0, At, B0); PG8_MMA(0, 1, At, B1); PG8_BAR; PG8_SCHED;
;             PG8_LDA(At, 0, 1); PG8_STAGE(PG8_SB(0, 0), b2, voffB); PG8_STAGE(PG8_SB(0, 1), b2 + hstep, voffB); PG8_STAGE(PG8_SA(0, 0), a2, voffA);
;             PG8_WAIT_V(8); PG8_WAIT_L(0); PG8_BAR; PG8_MMA(1, 0, At, B0); PG8_MMA(1, 1, At, B1); PG8_BAR; PG8_SCHED;
.LBB0_266:
	s_add_u32 s28, s24, 0xfff80080
	s_addc_u32 s29, s25, -1
	s_and_b64 s[26:27], s[26:27], exec
	s_cselect_b32 s29, s17, s29
	s_cselect_b32 s28, s75, s28
	s_cselect_b32 s27, s15, s50
	s_cselect_b32 s26, s85, s23
	s_add_i32 s42, 0, 0x10000
	v_add_u32_e32 v134, s42, v161
	s_add_i32 s43, 0, 0x14000
	ds_read_b128 v[140:143], v134
	ds_read_b128 v[144:147], v134 offset:1024
	ds_read_b128 v[166:169], v134 offset:2048
	ds_read_b128 v[170:173], v134 offset:3072
	v_add_u32_e32 v134, s43, v161
	ds_read_b128 v[174:177], v134
	ds_read_b128 v[186:189], v134 offset:1024
	ds_read_b128 v[190:193], v134 offset:2048
	ds_read_b128 v[194:197], v134 offset:3072
	v_lshl_add_u64 v[134:135], s[24:25], 0, v[156:157]
	s_add_i32 m0, s37, 0xc000
	ds_read_b128 v[198:201], v165
	ds_read_b128 v[202:205], v165 offset:1024
	ds_read_b128 v[206:209], v165 offset:2048
	ds_read_b128 v[210:213], v165 offset:3072
	ds_read_b128 v[214:217], v165 offset:4096
	ds_read_b128 v[218:221], v165 offset:5120
	ds_read_b128 v[222:225], v165 offset:6144
	ds_read_b128 v[226:229], v165 offset:7168
	global_load_lds_dwordx4 v[134:135], off
	v_lshl_add_u64 v[134:135], s[24:25], 0, v[158:159]
	s_add_i32 m0, s37, 0xe000
	s_nop 0
	global_load_lds_dwordx4 v[134:135], off
	s_waitcnt vmcnt(8)
	s_waitcnt lgkmcnt(0)
	s_setprio 1
	s_barrier
	v_mfma_f32_16x16x32_bf16 v[134:137], v[140:143], v[198:201], v[136:139]
	v_mfma_f32_16x16x32_bf16 v[124:127], v[166:169], v[198:201], v[124:127]
	v_mfma_f32_16x16x32_bf16 v[112:115], v[140:143], v[206:209], v[112:115]
	v_mfma_f32_16x16x32_bf16 v[108:111], v[166:169], v[206:209], v[108:111]
	v_mfma_f32_16x16x32_bf16 v[96:99], v[140:143], v[214:217], v[96:99]
	v_mfma_f32_16x16x32_bf16 v[92:95], v[166:169], v[214:217], v[92:95]
	v_mfma_f32_16x16x32_bf16 v[80:83], v[140:143], v[222:225], v[80:83]
	v_mfma_f32_16x16x32_bf16 v[76:79], v[166:169], v[222:225], v[76:79]
	v_mfma_f32_16x16x32_bf16 v[134:137], v[144:147], v[202:205], v[134:137]
	v_mfma_f32_16x16x32_bf16 v[124:127], v[170:173], v[202:205], v[124:127]
	v_mfma_f32_16x16x32_bf16 v[112:115], v[144:147], v[210:213], v[112:115]
	v_mfma_f32_16x16x32_bf16 v[108:111], v[170:173], v[210:213], v[108:111]
	v_mfma_f32_16x16x32_bf16 v[96:99], v[144:147], v[218:221], v[96:99]
	v_mfma_f32_16x16x32_bf16 v[92:95], v[170:173], v[218:221], v[92:95]
	v_mfma_f32_16x16x32_bf16 v[80:83], v[144:147], v[226:229], v[80:83]
	v_mfma_f32_16x16x32_bf16 v[76:79], v[170:173], v[226:229], v[76:79]
	s_setprio 0
	s_setprio 1
	v_mfma_f32_16x16x32_bf16 v[120:123], v[174:177], v[198:201], v[120:123]
	v_mfma_f32_16x16x32_bf16 v[116:119], v[190:193], v[198:201], v[116:119]
	v_mfma_f32_16x16x32_bf16 v[104:107], v[174:177], v[206:209], v[104:107]
	v_mfma_f32_16x16x32_bf16 v[100:103], v[190:193], v[206:209], v[100:103]
	v_mfma_f32_16x16x32_bf16 v[88:91], v[174:177], v[214:217], v[88:91]
	v_mfma_f32_16x16x32_bf16 v[84:87], v[190:193], v[214:217], v[84:87]
	v_mfma_f32_16x16x32_bf16 v[72:75], v[174:177], v[222:225], v[72:75]
	v_mfma_f32_16x16x32_bf16 v[68:71], v[190:193], v[222:225], v[68:71]
	v_mfma_f32_16x16x32_bf16 v[120:123], v[186:189], v[202:205], v[120:123]
	v_mfma_f32_16x16x32_bf16 v[116:119], v[194:197], v[202:205], v[116:119]
	v_mfma_f32_16x16x32_bf16 v[104:107], v[186:189], v[210:213], v[104:107]
	v_mfma_f32_16x16x32_bf16 v[100:103], v[194:197], v[210:213], v[100:103]
	v_mfma_f32_16x16x32_bf16 v[88:91], v[186:189], v[218:221], v[88:91]
	v_mfma_f32_16x16x32_bf16 v[84:87], v[194:197], v[218:221], v[84:87]
	v_mfma_f32_16x16x32_bf16 v[72:75], v[186:189], v[226:229], v[72:75]
	v_mfma_f32_16x16x32_bf16 v[68:71], v[194:197], v[226:229], v[68:71]
	s_setprio 0
	s_barrier
	s_add_i32 s42, s42, s31
	v_lshl_add_u64 v[178:179], s[26:27], 0, v[2:3]
	s_mov_b32 m0, s42
	ds_read_b128 v[198:201], v165 offset:16384
	ds_read_b128 v[202:205], v165 offset:17408
	ds_read_b128 v[206:209], v165 offset:18432
	ds_read_b128 v[210:213], v165 offset:19456
	ds_read_b128 v[214:217], v165 offset:20480
	ds_read_b128 v[218:221], v165 offset:21504
	ds_read_b128 v[222:225], v165 offset:22528
	ds_read_b128 v[226:229], v165 offset:23552
	global_load_lds_dwordx4 v[178:179], off
	s_add_i32 m0, s42, 0x2000
	s_add_u32 s94, s26, 0x80000
	v_lshl_add_u64 v[180:181], s[26:27], 0, v[0:1]
	s_addc_u32 s95, s27, 0
	s_add_i32 s42, s43, s31
	global_load_lds_dwordx4 v[180:181], off
	v_lshl_add_u64 v[138:139], s[94:95], 0, v[2:3]
	s_mov_b32 m0, s42
	v_lshl_add_u64 v[182:183], s[28:29], 0, v[150:151]
	global_load_lds_dwordx4 v[138:139], off
	v_lshl_add_u64 v[138:139], s[94:95], 0, v[0:1]
	s_add_i32 m0, s42, 0x2000
	v_lshl_add_u64 v[230:231], s[28:29], 0, v[148:149]
	global_load_lds_dwordx4 v[138:139], off
	s_mov_b32 m0, s37
	s_nop 0
	global_load_lds_dwordx4 v[182:183], off
	s_mov_b32 m0, s39
	s_nop 0
	global_load_lds_dwordx4 v[230:231], off
	s_waitcnt vmcnt(8)
	s_waitcnt lgkmcnt(0)
	s_setprio 1
	s_barrier
; #define PG8_STAGE(bufoff, gbase, voff) do { _Pragma("unroll") for (int _i = 0; _i < 2; ++_i) \
;         __builtin_amdgcn_global_load_lds((const unsigned*)((const char*)(gbase) + (voff)[_i]), (PG8_LAS unsigned*)(lds + (bufoff) + ldsw + _i * 8192), 16, 0, 0); } while (0)
; #define PG8_LDA(dst, b, h) do { _Pragma("unroll") for (int m = 0; m < 4; ++m) _Pragma("unroll") for (int k = 0; k < 2; ++k) dst[m][k] = *(const PG8_LAS bf16x8*)(lds + PG8_SA(b, h) + aoff + m * 2048 + k * 1024); } while (0)
; #define PG8_LDB(dst, b, h) do { _Pragma("unroll") for (int n = 0; n < 2; ++n) _Pragma("unroll") for (int k = 0; k < 2; ++k) dst[n][k] = *(const PG8_LAS bf16x8*)(lds + PG8_SB(b, h) + boff + n * 2048 + k * 1024); } while (0)
; #define PG8_MMA(ai, bj, At, Bt) do { __builtin_amdgcn_s_setprio(1); _Pragma("unroll") for (int m = 0; m < 4; ++m) _Pragma("unroll") for (int n = 0; n < 2; ++n) _Pragma("unroll") for (int k = 0; k < 2; ++k) \
;         acc[ai][bj][m][n] = __builtin_amdgcn_mfma_f32_16x16x32_bf16(Bt[n][k], At[m][k], acc[ai][bj][m][n], 0, 0, 0); __builtin_amdgcn_s_setprio(0); } while (0)
; #define PG8_WAIT_V(n) asm volatile("s_waitcnt vmcnt(" #n ")" ::: "memory")
; #define PG8_WAIT_L(n) asm volatile("s_waitcnt lgkmcnt(" #n ")" ::: "memory")
; #define PG8_BAR __builtin_amdgcn_s_barrier()
; #define PG8_SCHED __builtin_amdgcn_sched_barrier(0)
; template <class Epi, class Sched, bool ALIGN_EPI = false, bool SP2 = false>
; __device__ __forceinline__ void gemm_phase(PG8_LAS unsigned char* lds, const Gemm g, const Sched& S, const Epi& E, const int tid) {
;     ...
;             PG8_WAIT_V(8); PG8_WAIT_L(0); PG8_BAR; PG8_MMA(1, 0, At, B0); PG8_MMA(1, 1, At, B1); PG8_BAR; PG8_SCHED;
;             PG8_LDB(B0, 1, 0); PG8_LDB(B1, 1, 1); PG8_SCHED; PG8_LDA(At, 1, 0); PG8_STAGE(PG8_SA(0, 1), a2 + hstep, voffA);
;             PG8_WAIT_V(8); PG8_WAIT_L(0); PG8_BAR; PG8_MMA(0, 0, At, B0); PG8_MMA(0, 1, At, B1); PG8_BAR; PG8_SCHED;
	v_mfma_f32_16x16x32_bf16 v[64:67], v[140:143], v[198:201], v[64:67]
	v_mfma_f32_16x16x32_bf16 v[60:63], v[166:169], v[198:201], v[60:63]
	v_mfma_f32_16x16x32_bf16 v[56:59], v[174:177], v[198:201], v[56:59]
	v_mfma_f32_16x16x32_bf16 v[52:55], v[190:193], v[198:201], v[52:55]
	v_mfma_f32_16x16x32_bf16 v[48:51], v[140:143], v[206:209], v[48:51]
	v_mfma_f32_16x16x32_bf16 v[44:47], v[166:169], v[206:209], v[44:47]
	v_mfma_f32_16x16x32_bf16 v[40:43], v[174:177], v[206:209], v[40:43]
	v_mfma_f32_16x16x32_bf16 v[36:39], v[190:193], v[206:209], v[36:39]
	v_mfma_f32_16x16x32_bf16 v[32:35], v[140:143], v[214:217], v[32:35]
	v_mfma_f32_16x16x32_bf16 v[28:31], v[166:169], v[214:217], v[28:31]
	v_mfma_f32_16x16x32_bf16 v[24:27], v[174:177], v[214:217], v[24:27]
	v_mfma_f32_16x16x32_bf16 v[20:23], v[190:193], v[214:217], v[20:23]
	v_mfma_f32_16x16x32_bf16 v[16:19], v[140:143], v[222:225], v[16:19]
	v_mfma_f32_16x16x32_bf16 v[12:15], v[166:169], v[222:225], v[12:15]
	v_mfma_f32_16x16x32_bf16 v[8:11], v[174:177], v[222:225], v[8:11]
	v_mfma_f32_16x16x32_bf16 v[4:7], v[190:193], v[222:225], v[4:7]
	s_setprio 0
	s_setprio 1
	v_mfma_f32_16x16x32_bf16 v[64:67], v[144:147], v[202:205], v[64:67]
	v_mfma_f32_16x16x32_bf16 v[60:63], v[170:173], v[202:205], v[60:63]
	v_mfma_f32_16x16x32_bf16 v[56:59], v[186:189], v[202:205], v[56:59]
	v_mfma_f32_16x16x32_bf16 v[52:55], v[194:197], v[202:205], v[52:55]
	v_mfma_f32_16x16x32_bf16 v[48:51], v[144:147], v[210:213], v[48:51]
	v_mfma_f32_16x16x32_bf16 v[44:47], v[170:173], v[210:213], v[44:47]
	v_mfma_f32_16x16x32_bf16 v[40:43], v[186:189], v[210:213], v[40:43]
	v_mfma_f32_16x16x32_bf16 v[36:39], v[194:197], v[210:213], v[36:39]
	v_mfma_f32_16x16x32_bf16 v[32:35], v[144:147], v[218:221], v[32:35]
	v_mfma_f32_16x16x32_bf16 v[28:31], v[170:173], v[218:221], v[28:31]
	v_mfma_f32_16x16x32_bf16 v[24:27], v[186:189], v[218:221], v[24:27]
	v_mfma_f32_16x16x32_bf16 v[20:23], v[194:197], v[218:221], v[20:23]
	v_mfma_f32_16x16x32_bf16 v[16:19], v[144:147], v[226:229], v[16:19]
	v_mfma_f32_16x16x32_bf16 v[12:15], v[170:173], v[226:229], v[12:15]
	v_mfma_f32_16x16x32_bf16 v[8:11], v[186:189], v[226:229], v[8:11]
	v_mfma_f32_16x16x32_bf16 v[4:7], v[194:197], v[226:229], v[4:7]
	s_setprio 0
	s_barrier
	s_add_i32 s42, 0, 0x18000
	v_add_u32_e32 v138, s42, v161
	s_add_i32 s43, 0, 0x1c000
	ds_read_b128 v[140:143], v138
	ds_read_b128 v[144:147], v138 offset:1024
	ds_read_b128 v[166:169], v138 offset:2048
	ds_read_b128 v[170:173], v138 offset:3072
	v_add_u32_e32 v138, s43, v161
	ds_read_b128 v[174:177], v138
	ds_read_b128 v[186:189], v138 offset:1024
	ds_read_b128 v[190:193], v138 offset:2048
	ds_read_b128 v[194:197], v138 offset:3072
	s_add_u32 s28, s28, 0x80000
	s_addc_u32 s29, s29, 0
	s_mov_b32 m0, s44
	v_lshl_add_u64 v[138:139], s[28:29], 0, v[150:151]
	ds_read_b128 v[198:201], v165 offset:32768
	ds_read_b128 v[202:205], v165 offset:33792
	ds_read_b128 v[206:209], v165 offset:34816
	ds_read_b128 v[210:213], v165 offset:35840
	ds_read_b128 v[214:217], v165 offset:36864
	ds_read_b128 v[218:221], v165 offset:37888
	ds_read_b128 v[222:225], v165 offset:38912
	ds_read_b128 v[226:229], v165 offset:39936
	global_load_lds_dwordx4 v[138:139], off
	v_lshl_add_u64 v[138:139], s[28:29], 0, v[148:149]
	s_mov_b32 m0, s48
	s_nop 0
	global_load_lds_dwordx4 v[138:139], off
	s_waitcnt vmcnt(8)
	s_waitcnt lgkmcnt(0)
	s_setprio 1
	s_barrier
	v_mfma_f32_16x16x32_bf16 v[134:137], v[140:143], v[198:201], v[134:137]
	v_mfma_f32_16x16x32_bf16 v[124:127], v[166:169], v[198:201], v[124:127]
	v_mfma_f32_16x16x32_bf16 v[112:115], v[140:143], v[206:209], v[112:115]
	v_mfma_f32_16x16x32_bf16 v[108:111], v[166:169], v[206:209], v[108:111]
	v_mfma_f32_16x16x32_bf16 v[96:99], v[140:143], v[214:217], v[96:99]
	v_mfma_f32_16x16x32_bf16 v[92:95], v[166:169], v[214:217], v[92:95]
	v_mfma_f32_16x16x32_bf16 v[80:83], v[140:143], v[222:225], v[80:83]
	v_mfma_f32_16x16x32_bf16 v[76:79], v[166:169], v[222:225], v[76:79]
	v_mfma_f32_16x16x32_bf16 v[136:139], v[144:147], v[202:205], v[134:137]
	v_mfma_f32_16x16x32_bf16 v[124:127], v[170:173], v[202:205], v[124:127]
	v_mfma_f32_16x16x32_bf16 v[112:115], v[144:147], v[210:213], v[112:115]
	v_mfma_f32_16x16x32_bf16 v[108:111], v[170:173], v[210:213], v[108:111]
	v_mfma_f32_16x16x32_bf16 v[96:99], v[144:147], v[218:221], v[96:99]
	v_mfma_f32_16x16x32_bf16 v[92:95], v[170:173], v[218:221], v[92:95]
	v_mfma_f32_16x16x32_bf16 v[80:83], v[144:147], v[226:229], v[80:83]
	v_mfma_f32_16x16x32_bf16 v[76:79], v[170:173], v[226:229], v[76:79]
	s_setprio 0
	s_setprio 1
	v_mfma_f32_16x16x32_bf16 v[120:123], v[174:177], v[198:201], v[120:123]
	v_mfma_f32_16x16x32_bf16 v[116:119], v[190:193], v[198:201], v[116:119]
	v_mfma_f32_16x16x32_bf16 v[104:107], v[174:177], v[206:209], v[104:107]
	v_mfma_f32_16x16x32_bf16 v[100:103], v[190:193], v[206:209], v[100:103]
	v_mfma_f32_16x16x32_bf16 v[88:91], v[174:177], v[214:217], v[88:91]
	v_mfma_f32_16x16x32_bf16 v[84:87], v[190:193], v[214:217], v[84:87]
	v_mfma_f32_16x16x32_bf16 v[72:75], v[174:177], v[222:225], v[72:75]
	v_mfma_f32_16x16x32_bf16 v[68:71], v[190:193], v[222:225], v[68:71]
	v_mfma_f32_16x16x32_bf16 v[120:123], v[186:189], v[202:205], v[120:123]
	v_mfma_f32_16x16x32_bf16 v[116:119], v[194:197], v[202:205], v[116:119]
	v_mfma_f32_16x16x32_bf16 v[104:107], v[186:189], v[210:213], v[104:107]
	v_mfma_f32_16x16x32_bf16 v[100:103], v[194:197], v[210:213], v[100:103]
	v_mfma_f32_16x16x32_bf16 v[88:91], v[186:189], v[218:221], v[88:91]
	v_mfma_f32_16x16x32_bf16 v[84:87], v[194:197], v[218:221], v[84:87]
	v_mfma_f32_16x16x32_bf16 v[72:75], v[186:189], v[226:229], v[72:75]
	v_mfma_f32_16x16x32_bf16 v[68:71], v[194:197], v[226:229], v[68:71]
	s_setprio 0
	s_barrier
; #define PG8_STAGE(bufoff, gbase, voff) do { _Pragma("unroll") for (int _i = 0; _i < 2; ++_i) \
;         __builtin_amdgcn_global_load_lds((const unsigned*)((const char*)(gbase) + (voff)[_i]), (PG8_LAS unsigned*)(lds + (bufoff) + ldsw + _i * 8192), 16, 0, 0); } while (0)
; #define PG8_LDA(dst, b, h) do { _Pragma("unroll") for (int m = 0; m < 4; ++m) _Pragma("unroll") for (int k = 0; k < 2; ++k) dst[m][k] = *(const PG8_LAS bf16x8*)(lds + PG8_SA(b, h) + aoff + m * 2048 + k * 1024); } while (0)
; #define PG8_MMA(ai, bj, At, Bt) do { __builtin_amdgcn_s_setprio(1); _Pragma("unroll") for (int m = 0; m < 4; ++m) _Pragma("unroll") for (int n = 0; n < 2; ++n) _Pragma("unroll") for (int k = 0; k < 2; ++k) \
;         acc[ai][bj][m][n] = __builtin_amdgcn_mfma_f32_16x16x32_bf16(Bt[n][k], At[m][k], acc[ai][bj][m][n], 0, 0, 0); __builtin_amdgcn_s_setprio(0); } while (0)
; #define PG8_WAIT_V(n) asm volatile("s_waitcnt vmcnt(" #n ")" ::: "memory")
; #define PG8_WAIT_L(n) asm volatile("s_waitcnt lgkmcnt(" #n ")" ::: "memory")
; #define PG8_BAR __builtin_amdgcn_s_barrier()
; #define PG8_SCHED __builtin_amdgcn_sched_barrier(0)
; template <class Epi, class Sched, bool ALIGN_EPI = false, bool SP2 = false>
; __device__ __forceinline__ void gemm_phase(PG8_LAS unsigned char* lds, const Gemm g, const Sched& S, const Epi& E, const int tid) {
;     ...
;             PG8_LDA(At, 1, 1); PG8_STAGE(PG8_SB(1, 0), b3, voffB); PG8_STAGE(PG8_SB(1, 1), b3 + hstep, voffB); PG8_STAGE(PG8_SA(1, 0), a3, voffA);
;             PG8_WAIT_V(8); PG8_WAIT_L(0); PG8_BAR; PG8_MMA(1, 0, At, B0); PG8_MMA(1, 1, At, B1); PG8_BAR; PG8_SCHED;
	s_add_i32 s28, s42, s31
	v_lshl_add_u64 v[134:135], v[178:179], 0, s[46:47]
	s_mov_b32 m0, s28
	ds_read_b128 v[198:201], v165 offset:49152
	ds_read_b128 v[202:205], v165 offset:50176
	ds_read_b128 v[206:209], v165 offset:51200
	ds_read_b128 v[210:213], v165 offset:52224
	ds_read_b128 v[214:217], v165 offset:53248
	ds_read_b128 v[218:221], v165 offset:54272
	ds_read_b128 v[222:225], v165 offset:55296
	ds_read_b128 v[226:229], v165 offset:56320
	global_load_lds_dwordx4 v[134:135], off
	s_add_i32 m0, s28, 0x2000
	s_add_u32 s26, s26, 0x80080
	v_lshl_add_u64 v[134:135], v[180:181], 0, s[46:47]
	s_addc_u32 s27, s27, 0
	s_add_i32 s28, s43, s31
	global_load_lds_dwordx4 v[134:135], off
	v_lshl_add_u64 v[134:135], s[26:27], 0, v[2:3]
	s_mov_b32 m0, s28
	s_nop 0
	global_load_lds_dwordx4 v[134:135], off
	v_lshl_add_u64 v[134:135], s[26:27], 0, v[0:1]
	s_add_i32 m0, s28, 0x2000
	s_nop 0
	global_load_lds_dwordx4 v[134:135], off
	v_lshl_add_u64 v[134:135], v[182:183], 0, s[46:47]
	s_mov_b32 m0, s52
	s_nop 0
	global_load_lds_dwordx4 v[134:135], off
	v_lshl_add_u64 v[134:135], v[230:231], 0, s[46:47]
	s_mov_b32 m0, s53
	s_nop 0
	global_load_lds_dwordx4 v[134:135], off
	s_waitcnt vmcnt(8)
	s_waitcnt lgkmcnt(0)
	s_setprio 1
	s_barrier
	v_mfma_f32_16x16x32_bf16 v[64:67], v[140:143], v[198:201], v[64:67]
	v_mfma_f32_16x16x32_bf16 v[60:63], v[166:169], v[198:201], v[60:63]
	v_mfma_f32_16x16x32_bf16 v[56:59], v[174:177], v[198:201], v[56:59]
	v_mfma_f32_16x16x32_bf16 v[52:55], v[190:193], v[198:201], v[52:55]
	v_mfma_f32_16x16x32_bf16 v[48:51], v[140:143], v[206:209], v[48:51]
	v_mfma_f32_16x16x32_bf16 v[44:47], v[166:169], v[206:209], v[44:47]
	v_mfma_f32_16x16x32_bf16 v[40:43], v[174:177], v[206:209], v[40:43]
	v_mfma_f32_16x16x32_bf16 v[36:39], v[190:193], v[206:209], v[36:39]
	v_mfma_f32_16x16x32_bf16 v[32:35], v[140:143], v[214:217], v[32:35]
	v_mfma_f32_16x16x32_bf16 v[28:31], v[166:169], v[214:217], v[28:31]
	v_mfma_f32_16x16x32_bf16 v[24:27], v[174:177], v[214:217], v[24:27]
	v_mfma_f32_16x16x32_bf16 v[20:23], v[190:193], v[214:217], v[20:23]
	v_mfma_f32_16x16x32_bf16 v[16:19], v[140:143], v[222:225], v[16:19]
	v_mfma_f32_16x16x32_bf16 v[12:15], v[166:169], v[222:225], v[12:15]
	v_mfma_f32_16x16x32_bf16 v[8:11], v[174:177], v[222:225], v[8:11]
	v_mfma_f32_16x16x32_bf16 v[4:7], v[190:193], v[222:225], v[4:7]
	s_setprio 0
	s_setprio 1
	v_mfma_f32_16x16x32_bf16 v[64:67], v[144:147], v[202:205], v[64:67]
	v_mfma_f32_16x16x32_bf16 v[60:63], v[170:173], v[202:205], v[60:63]
	v_mfma_f32_16x16x32_bf16 v[56:59], v[186:189], v[202:205], v[56:59]
	v_mfma_f32_16x16x32_bf16 v[52:55], v[194:197], v[202:205], v[52:55]
	v_mfma_f32_16x16x32_bf16 v[48:51], v[144:147], v[210:213], v[48:51]
	v_mfma_f32_16x16x32_bf16 v[44:47], v[170:173], v[210:213], v[44:47]
	v_mfma_f32_16x16x32_bf16 v[40:43], v[186:189], v[210:213], v[40:43]
	v_mfma_f32_16x16x32_bf16 v[36:39], v[194:197], v[210:213], v[36:39]
	v_mfma_f32_16x16x32_bf16 v[32:35], v[144:147], v[218:221], v[32:35]
	v_mfma_f32_16x16x32_bf16 v[28:31], v[170:173], v[218:221], v[28:31]
	v_mfma_f32_16x16x32_bf16 v[24:27], v[186:189], v[218:221], v[24:27]
	v_mfma_f32_16x16x32_bf16 v[20:23], v[194:197], v[218:221], v[20:23]
	v_mfma_f32_16x16x32_bf16 v[16:19], v[144:147], v[226:229], v[16:19]
	v_mfma_f32_16x16x32_bf16 v[12:15], v[170:173], v[226:229], v[12:15]
	v_mfma_f32_16x16x32_bf16 v[8:11], v[186:189], v[226:229], v[8:11]
	v_mfma_f32_16x16x32_bf16 v[4:7], v[194:197], v[226:229], v[4:7]
	s_setprio 0
	s_barrier
	s_add_i32 s51, s51, 2
	s_add_u32 s24, s24, 0x100
	s_addc_u32 s25, s25, 0
	s_add_u32 s23, s23, 0x100
	s_addc_u32 s50, s50, 0
	s_cmp_gt_u32 s51, 29
	s_cbranch_scc1 .LBB0_269
